# cross-lane reductions in the P4 softmax epilogue and the conv LayerNorm: ds_bpermute butterflies replaced by DPP (xor 1,2,4,8) and v_permlane16/32_swap (xor 16,32), same pairwise sums
# baseline (speedup 1.0000x reference)
; #define LAS __attribute__((address_space(3)))
; __global__ void __launch_bounds__(NWAVES * 64, 2) mk_fwd(Args args) {
;     ...
;                     for (int k = 0; k < 8; ++k) { const int tok = wave * 8 + k; a[k] = *(const LAS f32x4*)(yt + tok * 512 + 4 * lane); c[k] = *(const LAS f32x4*)(yt + tok * 512 + 256 + 4 * lane);
;                         sm[k] = ((a[k][0] + a[k][1]) + (a[k][2] + a[k][3])) + ((c[k][0] + c[k][1]) + (c[k][2] + c[k][3])); }
; #pragma unroll
;                     for (int o = 1; o < 64; o <<= 1) {
; #pragma unroll
;                         for (int k = 0; k < 8; ++k) sm[k] += __shfl_xor(sm[k], o); }
.LBB0_354:
	s_barrier
	ds_read_b128 v[76:79], v168
	ds_read_b128 v[72:75], v168 offset:1024
	ds_read_b128 v[68:71], v168 offset:2048
	ds_read_b128 v[64:67], v168 offset:3072
	ds_read_b128 v[60:63], v168 offset:4096
	ds_read_b128 v[56:59], v168 offset:5120
	ds_read_b128 v[52:55], v168 offset:6144
	ds_read_b128 v[48:51], v168 offset:7168
	s_waitcnt lgkmcnt(7)
	v_mov_b32_e32 v16, v76
	s_waitcnt lgkmcnt(6)
	v_mov_b32_e32 v17, v72
	v_mov_b32_e32 v18, v77
	v_mov_b32_e32 v19, v73
	v_pk_add_f32 v[16:17], v[16:17], v[18:19]
	v_mov_b32_e32 v18, v78
	v_mov_b32_e32 v19, v74
	v_mov_b32_e32 v20, v79
	v_mov_b32_e32 v21, v75
	v_pk_add_f32 v[18:19], v[18:19], v[20:21]
	s_waitcnt lgkmcnt(5)
	v_mov_b32_e32 v20, v71
	v_pk_add_f32 v[16:17], v[16:17], v[18:19]
	v_mov_b32_e32 v18, v69
	v_add_f32_e32 v81, v16, v17
	v_mov_b32_e32 v16, v68
	s_waitcnt lgkmcnt(4)
	v_mov_b32_e32 v17, v64
	v_mov_b32_e32 v19, v65
	v_pk_add_f32 v[16:17], v[16:17], v[18:19]
	v_mov_b32_e32 v18, v70
	v_mov_b32_e32 v19, v66
	v_mov_b32_e32 v21, v67
	v_pk_add_f32 v[18:19], v[18:19], v[20:21]
	s_waitcnt lgkmcnt(3)
	v_mov_b32_e32 v20, v63
	v_pk_add_f32 v[16:17], v[16:17], v[18:19]
	v_mov_b32_e32 v18, v61
	v_add_f32_e32 v158, v16, v17
	v_mov_b32_e32 v16, v60
	s_waitcnt lgkmcnt(2)
	v_mov_b32_e32 v17, v56
	v_mov_b32_e32 v19, v57
	v_pk_add_f32 v[16:17], v[16:17], v[18:19]
	v_mov_b32_e32 v18, v62
	v_mov_b32_e32 v19, v58
	v_mov_b32_e32 v21, v59
	v_pk_add_f32 v[18:19], v[18:19], v[20:21]
	ds_read_b128 v[44:47], v168 offset:8192
	ds_read_b128 v[40:43], v168 offset:9216
	v_pk_add_f32 v[16:17], v[16:17], v[18:19]
	s_waitcnt lgkmcnt(3)
	v_mov_b32_e32 v18, v53
	v_add_f32_e32 v159, v16, v17
	v_mov_b32_e32 v16, v52
	s_waitcnt lgkmcnt(2)
	v_mov_b32_e32 v17, v48
	v_mov_b32_e32 v19, v49
	v_pk_add_f32 v[16:17], v[16:17], v[18:19]
	v_mov_b32_e32 v18, v54
	v_mov_b32_e32 v19, v50
	v_mov_b32_e32 v20, v55
	v_mov_b32_e32 v21, v51
	v_pk_add_f32 v[18:19], v[18:19], v[20:21]
	ds_read_b128 v[36:39], v168 offset:10240
	ds_read_b128 v[32:35], v168 offset:11264
	v_pk_add_f32 v[16:17], v[16:17], v[18:19]
	s_waitcnt lgkmcnt(3)
	v_mov_b32_e32 v18, v45
	v_add_f32_e32 v160, v16, v17
	v_mov_b32_e32 v16, v44
	s_waitcnt lgkmcnt(2)
	v_mov_b32_e32 v17, v40
	v_mov_b32_e32 v19, v41
	v_pk_add_f32 v[16:17], v[16:17], v[18:19]
	v_mov_b32_e32 v18, v46
	v_mov_b32_e32 v19, v42
	v_mov_b32_e32 v20, v47
	v_mov_b32_e32 v21, v43
	v_pk_add_f32 v[18:19], v[18:19], v[20:21]
	ds_read_b128 v[28:31], v168 offset:12288
	ds_read_b128 v[24:27], v168 offset:13312
	v_pk_add_f32 v[16:17], v[16:17], v[18:19]
	s_waitcnt lgkmcnt(3)
	v_mov_b32_e32 v18, v37
	v_add_f32_e32 v161, v16, v17
	v_mov_b32_e32 v16, v36
	s_waitcnt lgkmcnt(2)
	v_mov_b32_e32 v17, v32
	v_mov_b32_e32 v19, v33
	v_pk_add_f32 v[16:17], v[16:17], v[18:19]
	v_mov_b32_e32 v18, v38
	v_mov_b32_e32 v19, v34
	v_mov_b32_e32 v20, v39
	v_mov_b32_e32 v21, v35
	v_pk_add_f32 v[18:19], v[18:19], v[20:21]
	s_waitcnt lgkmcnt(1)
	v_mov_b32_e32 v154, v30
	v_pk_add_f32 v[16:17], v[16:17], v[18:19]
	v_mov_b32_e32 v18, v29
	v_add_f32_e32 v162, v16, v17
	v_mov_b32_e32 v16, v28
	s_waitcnt lgkmcnt(0)
	v_mov_b32_e32 v17, v24
	v_mov_b32_e32 v19, v25
	v_pk_add_f32 v[152:153], v[16:17], v[18:19]
	ds_read_b128 v[20:23], v168 offset:14336
	ds_read_b128 v[16:19], v168 offset:15360
	v_mov_b32_e32 v155, v26
	v_mov_b32_e32 v156, v31
	v_mov_b32_e32 v157, v27
	v_pk_add_f32 v[154:155], v[154:155], v[156:157]
	s_waitcnt lgkmcnt(1)
	v_mov_b32_e32 v156, v23
	v_pk_add_f32 v[152:153], v[152:153], v[154:155]
	v_mov_b32_e32 v154, v21
	v_add_f32_e32 v163, v152, v153
	v_mov_b32_e32 v152, v20
	s_waitcnt lgkmcnt(0)
	v_mov_b32_e32 v153, v16
	v_mov_b32_e32 v155, v17
	v_pk_add_f32 v[152:153], v[152:153], v[154:155]
	v_mov_b32_e32 v154, v22
	v_mov_b32_e32 v155, v18
	v_mov_b32_e32 v157, v19
	v_pk_add_f32 v[154:155], v[154:155], v[156:157]
	v_pk_add_f32 v[152:153], v[152:153], v[154:155]
	v_add_f32_e32 v152, v152, v153
	s_waitcnt lgkmcnt(3)
	v_add_f32_dpp v81, v81, v81 quad_perm:[1,0,3,2] row_mask:0xf bank_mask:0xf
	s_waitcnt lgkmcnt(2)
	v_add_f32_dpp v154, v159, v159 quad_perm:[1,0,3,2] row_mask:0xf bank_mask:0xf
	s_waitcnt lgkmcnt(3)
	v_add_f32_dpp v153, v158, v158 quad_perm:[1,0,3,2] row_mask:0xf bank_mask:0xf
	s_waitcnt lgkmcnt(4)
	v_add_f32_dpp v155, v160, v160 quad_perm:[1,0,3,2] row_mask:0xf bank_mask:0xf
	s_waitcnt lgkmcnt(3)
	v_add_f32_dpp v156, v161, v161 quad_perm:[1,0,3,2] row_mask:0xf bank_mask:0xf
	s_waitcnt lgkmcnt(2)
	v_add_f32_dpp v152, v152, v152 quad_perm:[1,0,3,2] row_mask:0xf bank_mask:0xf
	s_waitcnt lgkmcnt(3)
	v_add_f32_dpp v157, v162, v162 quad_perm:[1,0,3,2] row_mask:0xf bank_mask:0xf
	s_waitcnt lgkmcnt(2)
	v_add_f32_dpp v158, v163, v163 quad_perm:[1,0,3,2] row_mask:0xf bank_mask:0xf
	s_waitcnt lgkmcnt(4)
	v_add_f32_dpp v81, v81, v81 quad_perm:[2,3,0,1] row_mask:0xf bank_mask:0xf
	s_waitcnt lgkmcnt(3)
	v_add_f32_dpp v153, v153, v153 quad_perm:[2,3,0,1] row_mask:0xf bank_mask:0xf
	s_waitcnt lgkmcnt(4)
	v_add_f32_dpp v155, v155, v155 quad_perm:[2,3,0,1] row_mask:0xf bank_mask:0xf
	s_waitcnt lgkmcnt(3)
	v_add_f32_dpp v156, v156, v156 quad_perm:[2,3,0,1] row_mask:0xf bank_mask:0xf
	s_waitcnt lgkmcnt(4)
	v_add_f32_dpp v154, v154, v154 quad_perm:[2,3,0,1] row_mask:0xf bank_mask:0xf
	s_waitcnt lgkmcnt(4)
	v_add_f32_dpp v157, v157, v157 quad_perm:[2,3,0,1] row_mask:0xf bank_mask:0xf
	s_waitcnt lgkmcnt(3)
	v_add_f32_dpp v158, v158, v158 quad_perm:[2,3,0,1] row_mask:0xf bank_mask:0xf
	s_waitcnt lgkmcnt(4)
	v_add_f32_dpp v81, v81, v81 row_half_mirror row_mask:0xf bank_mask:0xf
	s_waitcnt lgkmcnt(3)
	v_add_f32_dpp v153, v153, v153 row_half_mirror row_mask:0xf bank_mask:0xf
	s_waitcnt lgkmcnt(4)
; __global__ void __launch_bounds__(NWAVES * 64, 2) mk_fwd(Args args) {
;     ...
;                     for (int o = 1; o < 64; o <<= 1) {
; #pragma unroll
;                         for (int k = 0; k < 8; ++k) sm[k] += __shfl_xor(sm[k], o); }
; #pragma unroll
;                     for (int k = 0; k < 8; ++k) { const float mu = sm[k] * (1.f / 512.f); a[k] = a[k] - mu; c[k] = c[k] - mu;
;                         sm[k] = ((a[k][0] * a[k][0] + a[k][1] * a[k][1]) + (a[k][2] * a[k][2] + a[k][3] * a[k][3])) + ((c[k][0] * c[k][0] + c[k][1] * c[k][1]) + (c[k][2] * c[k][2] + c[k][3] * c[k][3])); }
	v_add_f32_dpp v152, v152, v152 quad_perm:[2,3,0,1] row_mask:0xf bank_mask:0xf
	s_waitcnt lgkmcnt(4)
	v_add_f32_dpp v154, v154, v154 row_half_mirror row_mask:0xf bank_mask:0xf
	s_waitcnt lgkmcnt(3)
	v_add_f32_dpp v155, v155, v155 row_half_mirror row_mask:0xf bank_mask:0xf
	s_waitcnt lgkmcnt(4)
	v_add_f32_dpp v157, v157, v157 row_half_mirror row_mask:0xf bank_mask:0xf
	s_waitcnt lgkmcnt(3)
	v_add_f32_dpp v158, v158, v158 row_half_mirror row_mask:0xf bank_mask:0xf
	s_waitcnt lgkmcnt(4)
	v_add_f32_dpp v156, v156, v156 row_half_mirror row_mask:0xf bank_mask:0xf
	s_waitcnt lgkmcnt(4)
	v_add_f32_dpp v152, v152, v152 row_half_mirror row_mask:0xf bank_mask:0xf
	s_waitcnt lgkmcnt(3)
	v_add_f32_dpp v81, v81, v81 row_mirror row_mask:0xf bank_mask:0xf
	s_waitcnt lgkmcnt(4)
	v_add_f32_dpp v154, v154, v154 row_mirror row_mask:0xf bank_mask:0xf
	s_waitcnt lgkmcnt(3)
	v_add_f32_dpp v155, v155, v155 row_mirror row_mask:0xf bank_mask:0xf
	v_mov_b32_e32 v163, v81
	s_nop 1
	v_permlane16_swap_b32_e32 v81, v163
	s_waitcnt lgkmcnt(4)
	v_add_f32_dpp v153, v153, v153 row_mirror row_mask:0xf bank_mask:0xf
	s_waitcnt lgkmcnt(4)
	v_add_f32_dpp v156, v156, v156 row_mirror row_mask:0xf bank_mask:0xf
	s_waitcnt lgkmcnt(3)
	v_add_f32_dpp v157, v157, v157 row_mirror row_mask:0xf bank_mask:0xf
	v_mov_b32_e32 v159, v153
	s_nop 1
	v_permlane16_swap_b32_e32 v153, v159
	v_mov_b32_e32 v160, v154
	s_nop 1
	v_permlane16_swap_b32_e32 v154, v160
	s_waitcnt lgkmcnt(4)
	v_add_f32_dpp v152, v152, v152 row_mirror row_mask:0xf bank_mask:0xf
	s_waitcnt lgkmcnt(3)
	v_add_f32_e32 v81, v81, v163
	v_mov_b32_e32 v162, v156
	s_nop 1
	v_permlane16_swap_b32_e32 v156, v162
	v_mov_b32_e32 v163, v157
	s_nop 1
	v_permlane16_swap_b32_e32 v157, v163
	s_waitcnt lgkmcnt(4)
	v_add_f32_dpp v158, v158, v158 row_mirror row_mask:0xf bank_mask:0xf
	v_mov_b32_e32 v161, v155
	s_nop 1
	v_permlane16_swap_b32_e32 v155, v161
	s_waitcnt lgkmcnt(4)
	v_add_f32_e32 v153, v153, v159
	s_waitcnt lgkmcnt(3)
	v_add_f32_e32 v154, v154, v160
	s_waitcnt lgkmcnt(2)
	v_add_f32_e32 v156, v156, v162
	s_waitcnt lgkmcnt(1)
	v_add_f32_e32 v157, v157, v163
	v_mov_b32_e32 v159, v158
	s_nop 1
	v_permlane16_swap_b32_e32 v158, v159
	v_mov_b32_e32 v160, v152
	s_nop 1
	v_permlane16_swap_b32_e32 v152, v160
	v_mov_b32_e32 v162, v153
	s_nop 1
	v_permlane32_swap_b32_e32 v153, v162
	v_mov_b32_e32 v163, v154
	s_nop 1
	v_permlane32_swap_b32_e32 v154, v163
	s_waitcnt lgkmcnt(4)
	v_add_f32_e32 v155, v155, v161
	v_mov_b32_e32 v161, v81
	s_nop 1
	v_permlane32_swap_b32_e32 v81, v161
	s_waitcnt lgkmcnt(4)
	v_add_f32_e32 v158, v158, v159
	s_waitcnt lgkmcnt(3)
	v_add_f32_e32 v152, v152, v160
	s_waitcnt lgkmcnt(2)
	v_add_f32_e32 v159, v153, v162
	s_waitcnt lgkmcnt(1)
	v_add_f32_e32 v160, v154, v163
	v_mov_b32_e32 v153, v155
	s_nop 1
	v_permlane32_swap_b32_e32 v155, v153
	v_mov_b32_e32 v154, v156
	s_nop 1
	v_permlane32_swap_b32_e32 v156, v154
	s_waitcnt lgkmcnt(2)
	v_add_f32_e32 v81, v81, v161
	v_mov_b32_e32 v161, v157
	s_nop 1
	v_permlane32_swap_b32_e32 v157, v161
	v_mov_b32_e32 v162, v158
	s_nop 1
	v_permlane32_swap_b32_e32 v158, v162
	v_mov_b32_e32 v163, v152
	s_nop 1
	v_permlane32_swap_b32_e32 v152, v163
	v_fmamk_f32 v77, v81, 0xbb000000, v77
	v_fmamk_f32 v73, v81, 0xbb000000, v73
	s_waitcnt lgkmcnt(4)
	v_add_f32_e32 v164, v155, v153
	s_waitcnt lgkmcnt(3)
	v_add_f32_e32 v165, v156, v154
	v_fmamk_f32 v79, v81, 0xbb000000, v79
	v_fmac_f32_e32 v76, 0xbb000000, v81
	v_fmamk_f32 v75, v81, 0xbb000000, v75
	v_fmac_f32_e32 v72, 0xbb000000, v81
	v_mov_b32_e32 v154, v77
	v_mov_b32_e32 v155, v73
	s_waitcnt lgkmcnt(2)
	v_add_f32_e32 v161, v157, v161
	s_waitcnt lgkmcnt(1)
	v_add_f32_e32 v158, v158, v162
	s_waitcnt lgkmcnt(0)
	v_add_f32_e32 v162, v152, v163
	v_fmamk_f32 v78, v81, 0xbb000000, v78
	v_fmamk_f32 v74, v81, 0xbb000000, v74
	v_mov_b32_e32 v152, v76
	v_mov_b32_e32 v153, v72
	v_pk_mul_f32 v[154:155], v[154:155], v[154:155]
	v_mov_b32_e32 v156, v79
	v_mov_b32_e32 v157, v75
	v_pk_fma_f32 v[152:153], v[152:153], v[152:153], v[154:155]
	v_mov_b32_e32 v154, v78
	v_mov_b32_e32 v155, v74
	v_pk_mul_f32 v[156:157], v[156:157], v[156:157]
	v_fmamk_f32 v69, v159, 0xbb000000, v69
	v_pk_fma_f32 v[154:155], v[154:155], v[154:155], v[156:157]
	v_fmamk_f32 v65, v159, 0xbb000000, v65
	v_pk_add_f32 v[152:153], v[152:153], v[154:155]
	v_fmamk_f32 v71, v159, 0xbb000000, v71
	v_fmac_f32_e32 v68, 0xbb000000, v159
	v_fmamk_f32 v67, v159, 0xbb000000, v67
	v_fmac_f32_e32 v64, 0xbb000000, v159
	v_mov_b32_e32 v154, v69
	v_mov_b32_e32 v155, v65
	v_add_f32_e32 v81, v152, v153
	v_fmamk_f32 v70, v159, 0xbb000000, v70
	v_fmamk_f32 v66, v159, 0xbb000000, v66
	v_mov_b32_e32 v152, v68
	v_mov_b32_e32 v153, v64
	v_pk_mul_f32 v[154:155], v[154:155], v[154:155]
	v_mov_b32_e32 v156, v71
	v_mov_b32_e32 v157, v67
	v_pk_fma_f32 v[152:153], v[152:153], v[152:153], v[154:155]
	v_mov_b32_e32 v154, v70
	v_mov_b32_e32 v155, v66
	v_pk_mul_f32 v[156:157], v[156:157], v[156:157]
	v_fmamk_f32 v61, v160, 0xbb000000, v61
	v_pk_fma_f32 v[154:155], v[154:155], v[154:155], v[156:157]
	v_fmamk_f32 v57, v160, 0xbb000000, v57
	v_pk_add_f32 v[152:153], v[152:153], v[154:155]
	v_fmamk_f32 v63, v160, 0xbb000000, v63
	v_fmac_f32_e32 v60, 0xbb000000, v160
	v_fmamk_f32 v59, v160, 0xbb000000, v59
	v_fmac_f32_e32 v56, 0xbb000000, v160
	v_mov_b32_e32 v154, v61
	v_mov_b32_e32 v155, v57
	v_add_f32_e32 v159, v152, v153
	v_fmamk_f32 v62, v160, 0xbb000000, v62
	v_fmamk_f32 v58, v160, 0xbb000000, v58
	v_mov_b32_e32 v152, v60
	v_mov_b32_e32 v153, v56
	v_pk_mul_f32 v[154:155], v[154:155], v[154:155]
	v_mov_b32_e32 v156, v63
	v_mov_b32_e32 v157, v59
	v_pk_fma_f32 v[152:153], v[152:153], v[152:153], v[154:155]
	v_mov_b32_e32 v154, v62
; __global__ void __launch_bounds__(NWAVES * 64, 2) mk_fwd(Args args) {
;     ...
;                     for (int k = 0; k < 8; ++k) { const float mu = sm[k] * (1.f / 512.f); a[k] = a[k] - mu; c[k] = c[k] - mu;
;                         sm[k] = ((a[k][0] * a[k][0] + a[k][1] * a[k][1]) + (a[k][2] * a[k][2] + a[k][3] * a[k][3])) + ((c[k][0] * c[k][0] + c[k][1] * c[k][1]) + (c[k][2] * c[k][2] + c[k][3] * c[k][3])); }
; #pragma unroll
;                     for (int o = 1; o < 64; o <<= 1) {
; #pragma unroll
;                         for (int k = 0; k < 8; ++k) sm[k] += __shfl_xor(sm[k], o); }
	v_mov_b32_e32 v155, v58
	v_pk_mul_f32 v[156:157], v[156:157], v[156:157]
	v_fmamk_f32 v53, v164, 0xbb000000, v53
	v_pk_fma_f32 v[154:155], v[154:155], v[154:155], v[156:157]
	v_fmamk_f32 v49, v164, 0xbb000000, v49
	v_pk_add_f32 v[152:153], v[152:153], v[154:155]
	v_fmamk_f32 v55, v164, 0xbb000000, v55
	v_fmac_f32_e32 v52, 0xbb000000, v164
	v_fmamk_f32 v51, v164, 0xbb000000, v51
	v_fmac_f32_e32 v48, 0xbb000000, v164
	v_mov_b32_e32 v154, v53
	v_mov_b32_e32 v155, v49
	v_add_f32_e32 v160, v152, v153
	v_fmamk_f32 v54, v164, 0xbb000000, v54
	v_fmamk_f32 v50, v164, 0xbb000000, v50
	v_mov_b32_e32 v152, v52
	v_mov_b32_e32 v153, v48
	v_pk_mul_f32 v[154:155], v[154:155], v[154:155]
	v_mov_b32_e32 v156, v55
	v_mov_b32_e32 v157, v51
	v_pk_fma_f32 v[152:153], v[152:153], v[152:153], v[154:155]
	v_mov_b32_e32 v154, v54
	v_mov_b32_e32 v155, v50
	v_pk_mul_f32 v[156:157], v[156:157], v[156:157]
	v_fmamk_f32 v45, v165, 0xbb000000, v45
	v_pk_fma_f32 v[154:155], v[154:155], v[154:155], v[156:157]
	v_fmamk_f32 v41, v165, 0xbb000000, v41
	v_pk_add_f32 v[152:153], v[152:153], v[154:155]
	v_fmamk_f32 v47, v165, 0xbb000000, v47
	v_fmac_f32_e32 v44, 0xbb000000, v165
	v_fmamk_f32 v43, v165, 0xbb000000, v43
	v_fmac_f32_e32 v40, 0xbb000000, v165
	v_mov_b32_e32 v154, v45
	v_mov_b32_e32 v155, v41
	v_add_f32_e32 v163, v152, v153
	v_fmamk_f32 v46, v165, 0xbb000000, v46
	v_fmamk_f32 v42, v165, 0xbb000000, v42
	v_mov_b32_e32 v152, v44
	v_mov_b32_e32 v153, v40
	v_pk_mul_f32 v[154:155], v[154:155], v[154:155]
	v_mov_b32_e32 v156, v47
	v_mov_b32_e32 v157, v43
	v_pk_fma_f32 v[152:153], v[152:153], v[152:153], v[154:155]
	v_mov_b32_e32 v154, v46
	v_mov_b32_e32 v155, v42
	v_pk_mul_f32 v[156:157], v[156:157], v[156:157]
	v_fmamk_f32 v37, v161, 0xbb000000, v37
	v_pk_fma_f32 v[154:155], v[154:155], v[154:155], v[156:157]
	v_fmamk_f32 v33, v161, 0xbb000000, v33
	v_pk_add_f32 v[152:153], v[152:153], v[154:155]
	v_fmamk_f32 v39, v161, 0xbb000000, v39
	v_fmac_f32_e32 v36, 0xbb000000, v161
	v_fmamk_f32 v35, v161, 0xbb000000, v35
	v_fmac_f32_e32 v32, 0xbb000000, v161
	v_mov_b32_e32 v154, v37
	v_mov_b32_e32 v155, v33
	v_add_f32_e32 v164, v152, v153
	v_fmamk_f32 v38, v161, 0xbb000000, v38
	v_fmamk_f32 v34, v161, 0xbb000000, v34
	v_mov_b32_e32 v152, v36
	v_mov_b32_e32 v153, v32
	v_pk_mul_f32 v[154:155], v[154:155], v[154:155]
	v_mov_b32_e32 v156, v39
	v_mov_b32_e32 v157, v35
	v_pk_fma_f32 v[152:153], v[152:153], v[152:153], v[154:155]
	v_mov_b32_e32 v154, v38
	v_mov_b32_e32 v155, v34
	v_pk_mul_f32 v[156:157], v[156:157], v[156:157]
	v_fmamk_f32 v29, v158, 0xbb000000, v29
	v_pk_fma_f32 v[154:155], v[154:155], v[154:155], v[156:157]
	v_fmamk_f32 v25, v158, 0xbb000000, v25
	v_pk_add_f32 v[152:153], v[152:153], v[154:155]
	v_fmamk_f32 v31, v158, 0xbb000000, v31
	v_fmac_f32_e32 v28, 0xbb000000, v158
	v_fmamk_f32 v27, v158, 0xbb000000, v27
	v_fmac_f32_e32 v24, 0xbb000000, v158
	v_mov_b32_e32 v154, v29
	v_mov_b32_e32 v155, v25
	v_add_f32_e32 v161, v152, v153
	v_fmamk_f32 v30, v158, 0xbb000000, v30
	v_fmamk_f32 v26, v158, 0xbb000000, v26
	v_mov_b32_e32 v152, v28
	v_mov_b32_e32 v153, v24
	v_pk_mul_f32 v[154:155], v[154:155], v[154:155]
	v_mov_b32_e32 v156, v31
	v_mov_b32_e32 v157, v27
	v_pk_fma_f32 v[152:153], v[152:153], v[152:153], v[154:155]
	v_mov_b32_e32 v154, v30
	v_mov_b32_e32 v155, v26
	v_pk_mul_f32 v[156:157], v[156:157], v[156:157]
	v_fmamk_f32 v21, v162, 0xbb000000, v21
	v_pk_fma_f32 v[154:155], v[154:155], v[154:155], v[156:157]
	v_fmamk_f32 v17, v162, 0xbb000000, v17
	v_pk_add_f32 v[152:153], v[152:153], v[154:155]
	v_fmamk_f32 v23, v162, 0xbb000000, v23
	v_fmac_f32_e32 v20, 0xbb000000, v162
	v_fmamk_f32 v19, v162, 0xbb000000, v19
	v_fmac_f32_e32 v16, 0xbb000000, v162
	v_mov_b32_e32 v154, v21
	v_mov_b32_e32 v155, v17
	v_add_f32_e32 v158, v152, v153
	v_fmamk_f32 v22, v162, 0xbb000000, v22
	v_fmamk_f32 v18, v162, 0xbb000000, v18
	v_mov_b32_e32 v152, v20
	v_mov_b32_e32 v153, v16
	v_pk_mul_f32 v[154:155], v[154:155], v[154:155]
	v_mov_b32_e32 v156, v23
	v_mov_b32_e32 v157, v19
	v_pk_fma_f32 v[152:153], v[152:153], v[152:153], v[154:155]
	v_mov_b32_e32 v154, v22
	v_mov_b32_e32 v155, v18
	v_pk_mul_f32 v[156:157], v[156:157], v[156:157]
	s_add_i32 s4, s4, s14
	v_pk_fma_f32 v[154:155], v[154:155], v[154:155], v[156:157]
	v_pk_add_f32 v[152:153], v[152:153], v[154:155]
	v_add_f32_e32 v152, v152, v153
	s_ashr_i32 s5, s4, 31
	s_waitcnt lgkmcnt(2)
	v_add_f32_dpp v81, v81, v81 quad_perm:[1,0,3,2] row_mask:0xf bank_mask:0xf
	v_add_f32_dpp v153, v159, v159 quad_perm:[1,0,3,2] row_mask:0xf bank_mask:0xf
	s_waitcnt lgkmcnt(1)
	v_add_f32_dpp v154, v160, v160 quad_perm:[1,0,3,2] row_mask:0xf bank_mask:0xf
	v_add_f32_dpp v155, v163, v163 quad_perm:[1,0,3,2] row_mask:0xf bank_mask:0xf
	s_waitcnt lgkmcnt(3)
	v_add_f32_dpp v156, v164, v164 quad_perm:[1,0,3,2] row_mask:0xf bank_mask:0xf
	s_waitcnt lgkmcnt(4)
	v_add_f32_dpp v158, v158, v158 quad_perm:[1,0,3,2] row_mask:0xf bank_mask:0xf
	s_waitcnt lgkmcnt(3)
	v_add_f32_dpp v152, v152, v152 quad_perm:[1,0,3,2] row_mask:0xf bank_mask:0xf
	s_waitcnt lgkmcnt(3)
	v_add_f32_dpp v153, v153, v153 quad_perm:[2,3,0,1] row_mask:0xf bank_mask:0xf
	s_waitcnt lgkmcnt(4)
	v_add_f32_dpp v157, v161, v161 quad_perm:[1,0,3,2] row_mask:0xf bank_mask:0xf
	s_waitcnt lgkmcnt(3)
	v_add_f32_dpp v81, v81, v81 quad_perm:[2,3,0,1] row_mask:0xf bank_mask:0xf
	s_waitcnt lgkmcnt(4)
	v_add_f32_dpp v155, v155, v155 quad_perm:[2,3,0,1] row_mask:0xf bank_mask:0xf
	s_waitcnt lgkmcnt(4)
	v_add_f32_dpp v154, v154, v154 quad_perm:[2,3,0,1] row_mask:0xf bank_mask:0xf
	s_waitcnt lgkmcnt(3)
	v_add_f32_dpp v158, v158, v158 quad_perm:[2,3,0,1] row_mask:0xf bank_mask:0xf
	s_waitcnt lgkmcnt(4)
; __global__ void __launch_bounds__(NWAVES * 64, 2) mk_fwd(Args args) {
;     ...
;                     for (int o = 1; o < 64; o <<= 1) {
; #pragma unroll
;                         for (int k = 0; k < 8; ++k) sm[k] += __shfl_xor(sm[k], o); }
; #pragma unroll
;                     for (int k = 0; k < 8; ++k) { const int tok = wave * 8 + k; const float rstd = 1.0f / sqrtf(sm[k] * (1.f / 512.f) + EPS);
	v_add_f32_dpp v157, v157, v157 quad_perm:[2,3,0,1] row_mask:0xf bank_mask:0xf
	s_waitcnt lgkmcnt(4)
	v_add_f32_dpp v156, v156, v156 quad_perm:[2,3,0,1] row_mask:0xf bank_mask:0xf
	s_waitcnt lgkmcnt(4)
	v_add_f32_dpp v81, v81, v81 row_half_mirror row_mask:0xf bank_mask:0xf
	s_waitcnt lgkmcnt(4)
	v_add_f32_dpp v152, v152, v152 quad_perm:[2,3,0,1] row_mask:0xf bank_mask:0xf
	s_waitcnt lgkmcnt(3)
	v_add_f32_dpp v155, v155, v155 row_half_mirror row_mask:0xf bank_mask:0xf
	s_waitcnt lgkmcnt(4)
	v_add_f32_dpp v154, v154, v154 row_half_mirror row_mask:0xf bank_mask:0xf
	s_waitcnt lgkmcnt(4)
	v_add_f32_dpp v153, v153, v153 row_half_mirror row_mask:0xf bank_mask:0xf
	s_waitcnt lgkmcnt(4)
	v_add_f32_dpp v157, v157, v157 row_half_mirror row_mask:0xf bank_mask:0xf
	s_waitcnt lgkmcnt(4)
	v_add_f32_dpp v156, v156, v156 row_half_mirror row_mask:0xf bank_mask:0xf
	s_waitcnt lgkmcnt(3)
	v_add_f32_dpp v81, v81, v81 row_mirror row_mask:0xf bank_mask:0xf
	s_waitcnt lgkmcnt(4)
	v_add_f32_dpp v152, v152, v152 row_half_mirror row_mask:0xf bank_mask:0xf
	s_waitcnt lgkmcnt(3)
	v_add_f32_dpp v158, v158, v158 row_half_mirror row_mask:0xf bank_mask:0xf
	s_waitcnt lgkmcnt(3)
	v_add_f32_dpp v154, v154, v154 row_mirror row_mask:0xf bank_mask:0xf
	s_waitcnt lgkmcnt(3)
	v_add_f32_dpp v153, v153, v153 row_mirror row_mask:0xf bank_mask:0xf
	s_waitcnt lgkmcnt(2)
	v_add_f32_dpp v157, v157, v157 row_mirror row_mask:0xf bank_mask:0xf
	v_mov_b32_e32 v163, v154
	s_nop 1
	v_permlane16_swap_b32_e32 v154, v163
	s_waitcnt lgkmcnt(4)
	v_add_f32_dpp v155, v155, v155 row_mirror row_mask:0xf bank_mask:0xf
	v_mov_b32_e32 v161, v81
	s_nop 1
	v_permlane16_swap_b32_e32 v81, v161
	s_waitcnt lgkmcnt(4)
	v_add_f32_dpp v152, v152, v152 row_mirror row_mask:0xf bank_mask:0xf
	s_waitcnt lgkmcnt(3)
	v_add_f32_dpp v158, v158, v158 row_mirror row_mask:0xf bank_mask:0xf
	s_waitcnt lgkmcnt(2)
	v_add_f32_e32 v154, v154, v163
	v_mov_b32_e32 v159, v155
	s_nop 1
	v_permlane16_swap_b32_e32 v155, v159
	v_mov_b32_e32 v163, v152
	s_nop 1
	v_permlane16_swap_b32_e32 v152, v163
	s_waitcnt lgkmcnt(3)
	v_add_f32_dpp v156, v156, v156 row_mirror row_mask:0xf bank_mask:0xf
	v_mov_b32_e32 v162, v153
	s_nop 1
	v_permlane16_swap_b32_e32 v153, v162
	v_mov_b32_e32 v160, v156
	s_nop 1
	v_permlane16_swap_b32_e32 v156, v160
	s_waitcnt lgkmcnt(4)
	v_add_f32_e32 v81, v81, v161
	v_mov_b32_e32 v161, v157
	s_nop 1
	v_permlane16_swap_b32_e32 v157, v161
	s_waitcnt lgkmcnt(4)
	v_add_f32_e32 v155, v155, v159
	s_waitcnt lgkmcnt(3)
	v_add_f32_e32 v159, v152, v163
	v_mov_b32_e32 v152, v81
	s_nop 1
	v_permlane32_swap_b32_e32 v81, v152
	s_waitcnt lgkmcnt(3)
	v_add_f32_e32 v153, v153, v162
	s_waitcnt lgkmcnt(2)
	v_add_f32_e32 v156, v156, v160
	v_mov_b32_e32 v160, v153
	s_nop 1
	v_permlane32_swap_b32_e32 v153, v160
	v_mov_b32_e32 v162, v158
	s_nop 1
	v_permlane16_swap_b32_e32 v158, v162
	s_waitcnt lgkmcnt(3)
	v_add_f32_e32 v157, v157, v161
	v_mov_b32_e32 v161, v154
	s_nop 1
	v_permlane32_swap_b32_e32 v154, v161
	s_waitcnt lgkmcnt(3)
	v_add_f32_e32 v81, v81, v152
	v_fmamk_f32 v81, v81, 0x3b000000, v176
	s_waitcnt lgkmcnt(2)
	v_add_f32_e32 v160, v153, v160
	v_mul_f32_e32 v153, 0x4f800000, v81
	v_cmp_gt_f32_e32 vcc, s11, v81
	s_waitcnt lgkmcnt(1)
	v_add_f32_e32 v158, v158, v162
	v_mov_b32_e32 v162, v155
	s_nop 1
	v_permlane32_swap_b32_e32 v155, v162
	v_cndmask_b32_e32 v81, v81, v153, vcc
	v_mov_b32_e32 v163, v156
	s_nop 1
	v_permlane32_swap_b32_e32 v156, v163
	s_waitcnt lgkmcnt(2)
	v_add_f32_e32 v161, v154, v161
	v_sqrt_f32_e32 v154, v81
	s_waitcnt lgkmcnt(1)
	v_add_f32_e32 v155, v155, v162
	v_mov_b32_e32 v152, v157
	s_nop 1
	v_permlane32_swap_b32_e32 v157, v152
	s_waitcnt lgkmcnt(1)
	v_add_f32_e32 v156, v156, v163
	v_add_u32_e32 v162, -1, v154
	v_fma_f32 v163, -v162, v154, v81
	v_cmp_ge_f32_e64 s[2:3], 0, v163
	v_add_u32_e32 v163, 1, v154
	s_waitcnt lgkmcnt(0)
	v_add_f32_e32 v153, v157, v152
	v_cndmask_b32_e64 v162, v154, v162, s[2:3]
	v_fma_f32 v154, -v163, v154, v81
	v_cmp_lt_f32_e64 s[2:3], 0, v154
	v_mov_b32_e32 v157, v159
	s_nop 1
	v_permlane32_swap_b32_e32 v159, v157
	v_mov_b32_e32 v152, v158
	s_nop 1
	v_permlane32_swap_b32_e32 v158, v152
	v_cndmask_b32_e64 v154, v162, v163, s[2:3]
	v_mul_f32_e32 v162, 0x37800000, v154
	v_cndmask_b32_e32 v154, v154, v162, vcc
	v_cmp_class_f32_e32 vcc, v81, v177
	s_waitcnt lgkmcnt(0)
; __device__ __forceinline__ unsigned pk2(float lo, float hi) { return pg8::cvt_pk_bf16(lo, hi); }
; __global__ void __launch_bounds__(NWAVES * 64, 2) mk_fwd(Args args) {
;     ...
;                     for (int k = 0; k < 8; ++k) { const int tok = wave * 8 + k; const float rstd = 1.0f / sqrtf(sm[k] * (1.f / 512.f) + EPS);
;                         f32x4 x = a[k] * rstd * lg0 + lb0, y = c[k] * rstd * lg1 + lb1;
; #pragma unroll
;                         for (int e = 0; e < 4; ++e) { x[e] = x[e] * __builtin_amdgcn_rcpf(1.f + __builtin_amdgcn_exp2f(-LOG2E * x[e])); y[e] = y[e] * __builtin_amdgcn_rcpf(1.f + __builtin_amdgcn_exp2f(-LOG2E * y[e])); }
;                         bf16* orow = CAT + (size_t)(R0 + tok) * DM;
;                         *(v2u*)(orow + 4 * lane) = (v2u){pk2(x[0], x[1]), pk2(x[2], x[3])}; *(v2u*)(orow + 256 + 4 * lane) = (v2u){pk2(y[0], y[1]), pk2(y[2], y[3])}; }
	v_add_f32_e32 v152, v158, v152
	v_cndmask_b32_e32 v154, v154, v81, vcc
	v_div_scale_f32 v162, s[2:3], v154, v154, 1.0
	v_rcp_f32_e32 v163, v162
	v_add_f32_e32 v81, v159, v157
	s_lshl_b64 s[2:3], s[4:5], 11
	s_add_i32 s5, s6, s40
	v_fma_f32 v157, -v162, v163, 1.0
	v_fmac_f32_e32 v163, v157, v163
	v_div_scale_f32 v157, vcc, 1.0, v154, 1.0
	v_mul_f32_e32 v158, v157, v163
	v_fma_f32 v159, -v162, v158, v157
	v_fmac_f32_e32 v158, v159, v163
	v_fma_f32 v157, -v162, v158, v157
	v_div_fmas_f32 v157, v157, v163, v158
	v_div_fixup_f32 v154, v157, v154, 1.0
	v_pk_mul_f32 v[76:77], v[154:155], v[76:77] op_sel_hi:[0,1]
	v_pk_fma_f32 v[76:77], v[0:1], v[76:77], v[8:9]
	v_pk_mul_f32 v[72:73], v[154:155], v[72:73] op_sel_hi:[0,1]
	v_mul_f32_e32 v157, 0xbfb8aa3b, v76
	v_exp_f32_e32 v157, v157
	v_pk_fma_f32 v[72:73], v[4:5], v[72:73], v[12:13]
	v_pk_mul_f32 v[78:79], v[154:155], v[78:79] op_sel_hi:[0,1]
	v_pk_mul_f32 v[74:75], v[154:155], v[74:75] op_sel_hi:[0,1]
	v_add_f32_e32 v154, 1.0, v157
	v_mul_f32_e32 v157, 0xbfb8aa3b, v72
	v_mul_f32_e32 v158, 0xbfb8aa3b, v77
	v_exp_f32_e32 v157, v157
	v_exp_f32_e32 v158, v158
	v_mul_f32_e32 v159, 0xbfb8aa3b, v73
	v_rcp_f32_e32 v154, v154
	v_add_f32_e32 v157, 1.0, v157
	v_add_f32_e32 v158, 1.0, v158
	v_rcp_f32_e32 v157, v157
	v_rcp_f32_e32 v158, v158
	v_exp_f32_e32 v159, v159
	v_pk_fma_f32 v[78:79], v[2:3], v[78:79], v[10:11]
	v_pk_fma_f32 v[74:75], v[6:7], v[74:75], v[14:15]
	v_mul_f32_e32 v76, v76, v154
	v_mul_f32_e32 v154, v72, v157
	v_mul_f32_e32 v72, v77, v158
	v_add_f32_e32 v77, 1.0, v159
	v_mul_f32_e32 v157, 0xbfb8aa3b, v78
	v_mul_f32_e32 v158, 0xbfb8aa3b, v74
	v_rcp_f32_e32 v77, v77
	v_exp_f32_e32 v157, v157
	v_exp_f32_e32 v158, v158
	v_mul_f32_e32 v159, 0xbfb8aa3b, v75
	v_mul_f32_e32 v77, v73, v77
	v_add_f32_e32 v73, 1.0, v157
	v_add_f32_e32 v157, 1.0, v158
	v_mul_f32_e32 v158, 0xbfb8aa3b, v79
	v_exp_f32_e32 v158, v158
	v_exp_f32_e32 v159, v159
	v_rcp_f32_e32 v73, v73
	v_rcp_f32_e32 v157, v157
	v_add_f32_e32 v158, 1.0, v158
	v_add_f32_e32 v159, 1.0, v159
	v_rcp_f32_e32 v158, v158
	v_rcp_f32_e32 v159, v159
	v_mul_f32_e32 v73, v78, v73
	v_mul_f32_e32 v78, v74, v157
	v_mul_f32_e32 v74, v79, v158
	v_mul_f32_e32 v79, v75, v159
	v_fmamk_f32 v75, v160, 0x3b000000, v176
	v_cvt_pk_bf16_f32 v72, v76, v72
	v_mul_f32_e32 v76, 0x4f800000, v75
	v_cmp_gt_f32_e32 vcc, s11, v75
	v_cvt_pk_bf16_f32 v73, v73, v74
	s_nop 1
	v_cndmask_b32_e32 v76, v75, v76, vcc
	v_sqrt_f32_e32 v157, v76
	v_lshl_add_u64 v[74:75], v[148:149], 0, s[2:3]
	flat_store_dwordx2 v[74:75], v[72:73]
	v_add_u32_e32 v72, -1, v157
	v_fma_f32 v73, -v72, v157, v76
	v_cmp_ge_f32_e64 s[2:3], 0, v73
	v_add_u32_e32 v73, 1, v157
	s_nop 0
	v_cndmask_b32_e64 v72, v157, v72, s[2:3]
	v_fma_f32 v157, -v73, v157, v76
	v_cmp_lt_f32_e64 s[2:3], 0, v157
	s_nop 1
	v_cndmask_b32_e64 v72, v72, v73, s[2:3]
	v_mul_f32_e32 v73, 0x37800000, v72
	v_cndmask_b32_e32 v72, v72, v73, vcc
	v_cmp_class_f32_e32 vcc, v76, v177
	s_nop 1
	v_cndmask_b32_e32 v76, v72, v76, vcc
	v_div_scale_f32 v157, s[2:3], v76, v76, 1.0
	v_rcp_f32_e32 v158, v157
	v_cvt_pk_bf16_f32 v72, v154, v77
	v_cvt_pk_bf16_f32 v73, v78, v79
	flat_store_dwordx2 v[74:75], v[72:73] offset:512
	v_fma_f32 v72, -v157, v158, 1.0
	v_fmac_f32_e32 v158, v72, v158
	v_div_scale_f32 v72, vcc, 1.0, v76, 1.0
	v_mul_f32_e32 v73, v72, v158
	v_fma_f32 v74, -v157, v73, v72
	v_fmac_f32_e32 v73, v74, v158
	v_fma_f32 v72, -v157, v73, v72
	v_div_fmas_f32 v72, v72, v158, v73
	v_div_fixup_f32 v72, v72, v76, 1.0
	v_pk_mul_f32 v[68:69], v[72:73], v[68:69] op_sel_hi:[0,1]
	v_pk_fma_f32 v[68:69], v[0:1], v[68:69], v[8:9]
	v_pk_mul_f32 v[70:71], v[72:73], v[70:71] op_sel_hi:[0,1]
	v_pk_mul_f32 v[64:65], v[72:73], v[64:65] op_sel_hi:[0,1]
	v_mul_f32_e32 v73, 0xbfb8aa3b, v68
	v_exp_f32_e32 v73, v73
	v_pk_fma_f32 v[64:65], v[4:5], v[64:65], v[12:13]
	v_mul_f32_e32 v74, 0xbfb8aa3b, v69
	v_exp_f32_e32 v74, v74
	v_pk_mul_f32 v[66:67], v[72:73], v[66:67] op_sel_hi:[0,1]
	v_add_f32_e32 v72, 1.0, v73
	v_mul_f32_e32 v73, 0xbfb8aa3b, v64
	v_exp_f32_e32 v73, v73
	v_add_f32_e32 v74, 1.0, v74
	v_mul_f32_e32 v75, 0xbfb8aa3b, v65
	v_rcp_f32_e32 v72, v72
	v_add_f32_e32 v73, 1.0, v73
	v_rcp_f32_e32 v73, v73
	v_rcp_f32_e32 v74, v74
	v_exp_f32_e32 v75, v75
	v_pk_fma_f32 v[70:71], v[2:3], v[70:71], v[10:11]
	v_pk_fma_f32 v[66:67], v[6:7], v[66:67], v[14:15]
	v_mul_f32_e32 v68, v68, v72
	v_mul_f32_e32 v72, v64, v73
	v_mul_f32_e32 v64, v69, v74
	v_add_f32_e32 v69, 1.0, v75
	v_mul_f32_e32 v73, 0xbfb8aa3b, v70
	v_mul_f32_e32 v74, 0xbfb8aa3b, v66
	v_rcp_f32_e32 v69, v69
	v_exp_f32_e32 v73, v73
	v_exp_f32_e32 v74, v74
	v_mul_f32_e32 v75, 0xbfb8aa3b, v67
	v_mul_f32_e32 v69, v65, v69
	v_add_f32_e32 v65, 1.0, v73
	v_add_f32_e32 v73, 1.0, v74
	v_mul_f32_e32 v74, 0xbfb8aa3b, v71
	v_exp_f32_e32 v74, v74
	v_exp_f32_e32 v75, v75
	v_rcp_f32_e32 v65, v65
	v_rcp_f32_e32 v73, v73
	v_add_f32_e32 v74, 1.0, v74
	v_add_f32_e32 v75, 1.0, v75
	v_rcp_f32_e32 v74, v74
	v_rcp_f32_e32 v75, v75
	v_mul_f32_e32 v65, v70, v65
	v_mul_f32_e32 v70, v66, v73
	v_mul_f32_e32 v66, v71, v74
	v_mul_f32_e32 v71, v67, v75
	v_fmamk_f32 v67, v161, 0x3b000000, v176
	v_cvt_pk_bf16_f32 v64, v68, v64
	v_mul_f32_e32 v68, 0x4f800000, v67
	v_cmp_gt_f32_e32 vcc, s11, v67
	s_or_b32 s2, s4, 1
	s_ashr_i32 s3, s2, 31
	v_cndmask_b32_e32 v68, v67, v68, vcc
	v_sqrt_f32_e32 v73, v68
	s_lshl_b64 s[2:3], s[2:3], 11
	v_cvt_pk_bf16_f32 v65, v65, v66
	v_lshl_add_u64 v[66:67], v[148:149], 0, s[2:3]
	flat_store_dwordx2 v[66:67], v[64:65]
	v_add_u32_e32 v64, -1, v73
	v_fma_f32 v65, -v64, v73, v68
	v_cmp_ge_f32_e64 s[2:3], 0, v65
	v_add_u32_e32 v65, 1, v73
	s_nop 0
	v_cndmask_b32_e64 v64, v73, v64, s[2:3]
	v_fma_f32 v73, -v65, v73, v68
; __device__ __forceinline__ unsigned pk2(float lo, float hi) { return pg8::cvt_pk_bf16(lo, hi); }
; __global__ void __launch_bounds__(NWAVES * 64, 2) mk_fwd(Args args) {
;     ...
;                     for (int k = 0; k < 8; ++k) { const int tok = wave * 8 + k; const float rstd = 1.0f / sqrtf(sm[k] * (1.f / 512.f) + EPS);
;                         f32x4 x = a[k] * rstd * lg0 + lb0, y = c[k] * rstd * lg1 + lb1;
; #pragma unroll
;                         for (int e = 0; e < 4; ++e) { x[e] = x[e] * __builtin_amdgcn_rcpf(1.f + __builtin_amdgcn_exp2f(-LOG2E * x[e])); y[e] = y[e] * __builtin_amdgcn_rcpf(1.f + __builtin_amdgcn_exp2f(-LOG2E * y[e])); }
;                         bf16* orow = CAT + (size_t)(R0 + tok) * DM;
;                         *(v2u*)(orow + 4 * lane) = (v2u){pk2(x[0], x[1]), pk2(x[2], x[3])}; *(v2u*)(orow + 256 + 4 * lane) = (v2u){pk2(y[0], y[1]), pk2(y[2], y[3])}; }
	v_cmp_lt_f32_e64 s[2:3], 0, v73
	s_nop 1
	v_cndmask_b32_e64 v64, v64, v65, s[2:3]
	v_mul_f32_e32 v65, 0x37800000, v64
	v_cndmask_b32_e32 v64, v64, v65, vcc
	v_cmp_class_f32_e32 vcc, v68, v177
	s_nop 1
	v_cndmask_b32_e32 v68, v64, v68, vcc
	v_div_scale_f32 v73, s[2:3], v68, v68, 1.0
	v_rcp_f32_e32 v74, v73
	v_cvt_pk_bf16_f32 v64, v72, v69
	v_cvt_pk_bf16_f32 v65, v70, v71
	flat_store_dwordx2 v[66:67], v[64:65] offset:512
	v_fma_f32 v64, -v73, v74, 1.0
	v_fmac_f32_e32 v74, v64, v74
	v_div_scale_f32 v64, vcc, 1.0, v68, 1.0
	v_mul_f32_e32 v65, v64, v74
	v_fma_f32 v66, -v73, v65, v64
	v_fmac_f32_e32 v65, v66, v74
	v_fma_f32 v64, -v73, v65, v64
	v_div_fmas_f32 v64, v64, v74, v65
	v_div_fixup_f32 v64, v64, v68, 1.0
	v_pk_mul_f32 v[60:61], v[64:65], v[60:61] op_sel_hi:[0,1]
	v_pk_fma_f32 v[60:61], v[0:1], v[60:61], v[8:9]
	v_pk_mul_f32 v[62:63], v[64:65], v[62:63] op_sel_hi:[0,1]
	v_pk_mul_f32 v[56:57], v[64:65], v[56:57] op_sel_hi:[0,1]
	v_mul_f32_e32 v65, 0xbfb8aa3b, v60
	v_exp_f32_e32 v65, v65
	v_pk_fma_f32 v[56:57], v[4:5], v[56:57], v[12:13]
	v_mul_f32_e32 v66, 0xbfb8aa3b, v61
	v_exp_f32_e32 v66, v66
	v_pk_mul_f32 v[58:59], v[64:65], v[58:59] op_sel_hi:[0,1]
	v_add_f32_e32 v64, 1.0, v65
	v_mul_f32_e32 v65, 0xbfb8aa3b, v56
	v_exp_f32_e32 v65, v65
	v_add_f32_e32 v66, 1.0, v66
	v_mul_f32_e32 v67, 0xbfb8aa3b, v57
	v_rcp_f32_e32 v64, v64
	v_add_f32_e32 v65, 1.0, v65
	v_rcp_f32_e32 v65, v65
	v_rcp_f32_e32 v66, v66
	v_exp_f32_e32 v67, v67
	v_pk_fma_f32 v[62:63], v[2:3], v[62:63], v[10:11]
	v_pk_fma_f32 v[58:59], v[6:7], v[58:59], v[14:15]
	v_mul_f32_e32 v60, v60, v64
	v_mul_f32_e32 v64, v56, v65
	v_mul_f32_e32 v56, v61, v66
	v_add_f32_e32 v61, 1.0, v67
	v_mul_f32_e32 v65, 0xbfb8aa3b, v62
	v_mul_f32_e32 v66, 0xbfb8aa3b, v58
	v_rcp_f32_e32 v61, v61
	v_exp_f32_e32 v65, v65
	v_exp_f32_e32 v66, v66
	v_mul_f32_e32 v67, 0xbfb8aa3b, v59
	v_mul_f32_e32 v61, v57, v61
	v_add_f32_e32 v57, 1.0, v65
	v_add_f32_e32 v65, 1.0, v66
	v_mul_f32_e32 v66, 0xbfb8aa3b, v63
	v_exp_f32_e32 v66, v66
	v_exp_f32_e32 v67, v67
	v_rcp_f32_e32 v57, v57
	v_rcp_f32_e32 v65, v65
	v_add_f32_e32 v66, 1.0, v66
	v_add_f32_e32 v67, 1.0, v67
	v_rcp_f32_e32 v66, v66
	v_rcp_f32_e32 v67, v67
	v_mul_f32_e32 v57, v62, v57
	v_mul_f32_e32 v62, v58, v65
	v_mul_f32_e32 v58, v63, v66
	v_mul_f32_e32 v63, v59, v67
	v_fmamk_f32 v59, v155, 0x3b000000, v176
	v_cvt_pk_bf16_f32 v56, v60, v56
	v_mul_f32_e32 v60, 0x4f800000, v59
	v_cmp_gt_f32_e32 vcc, s11, v59
	s_or_b32 s2, s4, 2
	s_ashr_i32 s3, s2, 31
	v_cndmask_b32_e32 v60, v59, v60, vcc
	v_sqrt_f32_e32 v65, v60
	s_lshl_b64 s[2:3], s[2:3], 11
	v_cvt_pk_bf16_f32 v57, v57, v58
	v_lshl_add_u64 v[58:59], v[148:149], 0, s[2:3]
	flat_store_dwordx2 v[58:59], v[56:57]
	v_add_u32_e32 v56, -1, v65
	v_fma_f32 v57, -v56, v65, v60
	v_cmp_ge_f32_e64 s[2:3], 0, v57
	v_add_u32_e32 v57, 1, v65
	s_nop 0
	v_cndmask_b32_e64 v56, v65, v56, s[2:3]
	v_fma_f32 v65, -v57, v65, v60
	v_cmp_lt_f32_e64 s[2:3], 0, v65
	s_nop 1
	v_cndmask_b32_e64 v56, v56, v57, s[2:3]
	v_mul_f32_e32 v57, 0x37800000, v56
	v_cndmask_b32_e32 v56, v56, v57, vcc
	v_cmp_class_f32_e32 vcc, v60, v177
	s_nop 1
	v_cndmask_b32_e32 v60, v56, v60, vcc
	v_div_scale_f32 v65, s[2:3], v60, v60, 1.0
	v_rcp_f32_e32 v66, v65
	v_cvt_pk_bf16_f32 v56, v64, v61
	v_cvt_pk_bf16_f32 v57, v62, v63
	flat_store_dwordx2 v[58:59], v[56:57] offset:512
	v_fma_f32 v56, -v65, v66, 1.0
	v_fmac_f32_e32 v66, v56, v66
	v_div_scale_f32 v56, vcc, 1.0, v60, 1.0
	v_mul_f32_e32 v57, v56, v66
	v_fma_f32 v58, -v65, v57, v56
	v_fmac_f32_e32 v57, v58, v66
	v_fma_f32 v56, -v65, v57, v56
	v_div_fmas_f32 v56, v56, v66, v57
	v_div_fixup_f32 v56, v56, v60, 1.0
	v_pk_mul_f32 v[52:53], v[56:57], v[52:53] op_sel_hi:[0,1]
	v_pk_fma_f32 v[52:53], v[0:1], v[52:53], v[8:9]
	v_pk_mul_f32 v[54:55], v[56:57], v[54:55] op_sel_hi:[0,1]
	v_pk_mul_f32 v[48:49], v[56:57], v[48:49] op_sel_hi:[0,1]
	v_mul_f32_e32 v57, 0xbfb8aa3b, v52
	v_exp_f32_e32 v57, v57
	v_pk_fma_f32 v[48:49], v[4:5], v[48:49], v[12:13]
	v_mul_f32_e32 v58, 0xbfb8aa3b, v53
	v_exp_f32_e32 v58, v58
	v_pk_mul_f32 v[50:51], v[56:57], v[50:51] op_sel_hi:[0,1]
	v_add_f32_e32 v56, 1.0, v57
	v_mul_f32_e32 v57, 0xbfb8aa3b, v48
	v_exp_f32_e32 v57, v57
	v_add_f32_e32 v58, 1.0, v58
	v_mul_f32_e32 v59, 0xbfb8aa3b, v49
	v_rcp_f32_e32 v56, v56
	v_add_f32_e32 v57, 1.0, v57
	v_rcp_f32_e32 v57, v57
	v_rcp_f32_e32 v58, v58
	v_exp_f32_e32 v59, v59
	v_pk_fma_f32 v[54:55], v[2:3], v[54:55], v[10:11]
	v_pk_fma_f32 v[50:51], v[6:7], v[50:51], v[14:15]
	v_mul_f32_e32 v52, v52, v56
	v_mul_f32_e32 v56, v48, v57
	v_mul_f32_e32 v48, v53, v58
	v_add_f32_e32 v53, 1.0, v59
	v_mul_f32_e32 v57, 0xbfb8aa3b, v54
	v_mul_f32_e32 v58, 0xbfb8aa3b, v50
	v_rcp_f32_e32 v53, v53
	v_exp_f32_e32 v57, v57
	v_exp_f32_e32 v58, v58
	v_mul_f32_e32 v59, 0xbfb8aa3b, v51
	v_mul_f32_e32 v53, v49, v53
	v_add_f32_e32 v49, 1.0, v57
	v_add_f32_e32 v57, 1.0, v58
	v_mul_f32_e32 v58, 0xbfb8aa3b, v55
	v_exp_f32_e32 v58, v58
	v_exp_f32_e32 v59, v59
	v_rcp_f32_e32 v49, v49
	v_rcp_f32_e32 v57, v57
	v_add_f32_e32 v58, 1.0, v58
	v_add_f32_e32 v59, 1.0, v59
	v_rcp_f32_e32 v58, v58
	v_rcp_f32_e32 v59, v59
	v_mul_f32_e32 v49, v54, v49
	v_mul_f32_e32 v54, v50, v57
	v_mul_f32_e32 v50, v55, v58
	v_mul_f32_e32 v55, v51, v59
	v_fmamk_f32 v51, v156, 0x3b000000, v176
	v_cvt_pk_bf16_f32 v48, v52, v48
	v_mul_f32_e32 v52, 0x4f800000, v51
	v_cmp_gt_f32_e32 vcc, s11, v51
	s_or_b32 s2, s4, 3
	s_ashr_i32 s3, s2, 31
	v_cndmask_b32_e32 v52, v51, v52, vcc
	v_sqrt_f32_e32 v57, v52
	s_lshl_b64 s[2:3], s[2:3], 11
	v_cvt_pk_bf16_f32 v49, v49, v50
	v_lshl_add_u64 v[50:51], v[148:149], 0, s[2:3]
	flat_store_dwordx2 v[50:51], v[48:49]
	v_add_u32_e32 v48, -1, v57
	v_fma_f32 v49, -v48, v57, v52
; __device__ __forceinline__ unsigned pk2(float lo, float hi) { return pg8::cvt_pk_bf16(lo, hi); }
; __global__ void __launch_bounds__(NWAVES * 64, 2) mk_fwd(Args args) {
;     ...
;                     for (int k = 0; k < 8; ++k) { const int tok = wave * 8 + k; const float rstd = 1.0f / sqrtf(sm[k] * (1.f / 512.f) + EPS);
;                         f32x4 x = a[k] * rstd * lg0 + lb0, y = c[k] * rstd * lg1 + lb1;
; #pragma unroll
;                         for (int e = 0; e < 4; ++e) { x[e] = x[e] * __builtin_amdgcn_rcpf(1.f + __builtin_amdgcn_exp2f(-LOG2E * x[e])); y[e] = y[e] * __builtin_amdgcn_rcpf(1.f + __builtin_amdgcn_exp2f(-LOG2E * y[e])); }
;                         bf16* orow = CAT + (size_t)(R0 + tok) * DM;
;                         *(v2u*)(orow + 4 * lane) = (v2u){pk2(x[0], x[1]), pk2(x[2], x[3])}; *(v2u*)(orow + 256 + 4 * lane) = (v2u){pk2(y[0], y[1]), pk2(y[2], y[3])}; }
	v_cmp_ge_f32_e64 s[2:3], 0, v49
	v_add_u32_e32 v49, 1, v57
	s_nop 0
	v_cndmask_b32_e64 v48, v57, v48, s[2:3]
	v_fma_f32 v57, -v49, v57, v52
	v_cmp_lt_f32_e64 s[2:3], 0, v57
	s_nop 1
	v_cndmask_b32_e64 v48, v48, v49, s[2:3]
	v_mul_f32_e32 v49, 0x37800000, v48
	v_cndmask_b32_e32 v48, v48, v49, vcc
	v_cmp_class_f32_e32 vcc, v52, v177
	s_nop 1
	v_cndmask_b32_e32 v52, v48, v52, vcc
	v_div_scale_f32 v57, s[2:3], v52, v52, 1.0
	v_rcp_f32_e32 v58, v57
	v_cvt_pk_bf16_f32 v48, v56, v53
	v_cvt_pk_bf16_f32 v49, v54, v55
	flat_store_dwordx2 v[50:51], v[48:49] offset:512
	v_fma_f32 v48, -v57, v58, 1.0
	v_fmac_f32_e32 v58, v48, v58
	v_div_scale_f32 v48, vcc, 1.0, v52, 1.0
	v_mul_f32_e32 v49, v48, v58
	v_fma_f32 v50, -v57, v49, v48
	v_fmac_f32_e32 v49, v50, v58
	v_fma_f32 v48, -v57, v49, v48
	v_div_fmas_f32 v48, v48, v58, v49
	v_div_fixup_f32 v48, v48, v52, 1.0
	v_pk_mul_f32 v[44:45], v[48:49], v[44:45] op_sel_hi:[0,1]
	v_pk_fma_f32 v[44:45], v[0:1], v[44:45], v[8:9]
	v_pk_mul_f32 v[46:47], v[48:49], v[46:47] op_sel_hi:[0,1]
	v_pk_mul_f32 v[40:41], v[48:49], v[40:41] op_sel_hi:[0,1]
	v_mul_f32_e32 v49, 0xbfb8aa3b, v44
	v_exp_f32_e32 v49, v49
	v_pk_fma_f32 v[40:41], v[4:5], v[40:41], v[12:13]
	v_mul_f32_e32 v50, 0xbfb8aa3b, v45
	v_exp_f32_e32 v50, v50
	v_pk_mul_f32 v[42:43], v[48:49], v[42:43] op_sel_hi:[0,1]
	v_add_f32_e32 v48, 1.0, v49
	v_mul_f32_e32 v49, 0xbfb8aa3b, v40
	v_exp_f32_e32 v49, v49
	v_add_f32_e32 v50, 1.0, v50
	v_mul_f32_e32 v51, 0xbfb8aa3b, v41
	v_rcp_f32_e32 v48, v48
	v_add_f32_e32 v49, 1.0, v49
	v_rcp_f32_e32 v49, v49
	v_rcp_f32_e32 v50, v50
	v_exp_f32_e32 v51, v51
	v_pk_fma_f32 v[46:47], v[2:3], v[46:47], v[10:11]
	v_pk_fma_f32 v[42:43], v[6:7], v[42:43], v[14:15]
	v_mul_f32_e32 v44, v44, v48
	v_mul_f32_e32 v48, v40, v49
	v_mul_f32_e32 v40, v45, v50
	v_add_f32_e32 v45, 1.0, v51
	v_mul_f32_e32 v49, 0xbfb8aa3b, v46
	v_mul_f32_e32 v50, 0xbfb8aa3b, v42
	v_rcp_f32_e32 v45, v45
	v_exp_f32_e32 v49, v49
	v_exp_f32_e32 v50, v50
	v_mul_f32_e32 v51, 0xbfb8aa3b, v43
	v_mul_f32_e32 v45, v41, v45
	v_add_f32_e32 v41, 1.0, v49
	v_add_f32_e32 v49, 1.0, v50
	v_mul_f32_e32 v50, 0xbfb8aa3b, v47
	v_exp_f32_e32 v50, v50
	v_exp_f32_e32 v51, v51
	v_rcp_f32_e32 v41, v41
	v_rcp_f32_e32 v49, v49
	v_add_f32_e32 v50, 1.0, v50
	v_add_f32_e32 v51, 1.0, v51
	v_rcp_f32_e32 v50, v50
	v_rcp_f32_e32 v51, v51
	v_mul_f32_e32 v41, v46, v41
	v_mul_f32_e32 v46, v42, v49
	v_mul_f32_e32 v42, v47, v50
	v_mul_f32_e32 v47, v43, v51
	v_fmamk_f32 v43, v153, 0x3b000000, v176
	v_cvt_pk_bf16_f32 v40, v44, v40
	v_mul_f32_e32 v44, 0x4f800000, v43
	v_cmp_gt_f32_e32 vcc, s11, v43
	s_or_b32 s2, s4, 4
	s_ashr_i32 s3, s2, 31
	v_cndmask_b32_e32 v44, v43, v44, vcc
	v_sqrt_f32_e32 v49, v44
	s_lshl_b64 s[2:3], s[2:3], 11
	v_cvt_pk_bf16_f32 v41, v41, v42
	v_lshl_add_u64 v[42:43], v[148:149], 0, s[2:3]
	flat_store_dwordx2 v[42:43], v[40:41]
	v_add_u32_e32 v40, -1, v49
	v_fma_f32 v41, -v40, v49, v44
	v_cmp_ge_f32_e64 s[2:3], 0, v41
	v_add_u32_e32 v41, 1, v49
	s_nop 0
	v_cndmask_b32_e64 v40, v49, v40, s[2:3]
	v_fma_f32 v49, -v41, v49, v44
	v_cmp_lt_f32_e64 s[2:3], 0, v49
	s_nop 1
	v_cndmask_b32_e64 v40, v40, v41, s[2:3]
	v_mul_f32_e32 v41, 0x37800000, v40
	v_cndmask_b32_e32 v40, v40, v41, vcc
	v_cmp_class_f32_e32 vcc, v44, v177
	s_nop 1
	v_cndmask_b32_e32 v44, v40, v44, vcc
	v_div_scale_f32 v49, s[2:3], v44, v44, 1.0
	v_rcp_f32_e32 v50, v49
	v_cvt_pk_bf16_f32 v40, v48, v45
	v_cvt_pk_bf16_f32 v41, v46, v47
	flat_store_dwordx2 v[42:43], v[40:41] offset:512
	v_fma_f32 v40, -v49, v50, 1.0
	v_fmac_f32_e32 v50, v40, v50
	v_div_scale_f32 v40, vcc, 1.0, v44, 1.0
	v_mul_f32_e32 v41, v40, v50
	v_fma_f32 v42, -v49, v41, v40
	v_fmac_f32_e32 v41, v42, v50
	v_fma_f32 v40, -v49, v41, v40
	v_div_fmas_f32 v40, v40, v50, v41
	v_div_fixup_f32 v40, v40, v44, 1.0
	v_pk_mul_f32 v[36:37], v[40:41], v[36:37] op_sel_hi:[0,1]
	v_pk_fma_f32 v[36:37], v[0:1], v[36:37], v[8:9]
	v_pk_mul_f32 v[38:39], v[40:41], v[38:39] op_sel_hi:[0,1]
	v_pk_mul_f32 v[32:33], v[40:41], v[32:33] op_sel_hi:[0,1]
	v_mul_f32_e32 v41, 0xbfb8aa3b, v36
	v_exp_f32_e32 v41, v41
	v_pk_fma_f32 v[32:33], v[4:5], v[32:33], v[12:13]
	v_mul_f32_e32 v42, 0xbfb8aa3b, v37
	v_exp_f32_e32 v42, v42
	v_pk_mul_f32 v[34:35], v[40:41], v[34:35] op_sel_hi:[0,1]
	v_add_f32_e32 v40, 1.0, v41
	v_mul_f32_e32 v41, 0xbfb8aa3b, v32
	v_exp_f32_e32 v41, v41
	v_add_f32_e32 v42, 1.0, v42
	v_mul_f32_e32 v43, 0xbfb8aa3b, v33
	v_rcp_f32_e32 v40, v40
	v_add_f32_e32 v41, 1.0, v41
	v_rcp_f32_e32 v41, v41
	v_rcp_f32_e32 v42, v42
	v_exp_f32_e32 v43, v43
	v_pk_fma_f32 v[38:39], v[2:3], v[38:39], v[10:11]
	v_pk_fma_f32 v[34:35], v[6:7], v[34:35], v[14:15]
	v_mul_f32_e32 v36, v36, v40
	v_mul_f32_e32 v40, v32, v41
	v_mul_f32_e32 v32, v37, v42
	v_add_f32_e32 v37, 1.0, v43
	v_mul_f32_e32 v41, 0xbfb8aa3b, v38
	v_mul_f32_e32 v42, 0xbfb8aa3b, v34
	v_rcp_f32_e32 v37, v37
	v_exp_f32_e32 v41, v41
	v_exp_f32_e32 v42, v42
	v_mul_f32_e32 v43, 0xbfb8aa3b, v35
	v_mul_f32_e32 v37, v33, v37
	v_add_f32_e32 v33, 1.0, v41
	v_add_f32_e32 v41, 1.0, v42
	v_mul_f32_e32 v42, 0xbfb8aa3b, v39
	v_exp_f32_e32 v42, v42
	v_exp_f32_e32 v43, v43
	v_rcp_f32_e32 v33, v33
	v_rcp_f32_e32 v41, v41
	v_add_f32_e32 v42, 1.0, v42
	v_add_f32_e32 v43, 1.0, v43
	v_rcp_f32_e32 v42, v42
	v_rcp_f32_e32 v43, v43
	v_mul_f32_e32 v33, v38, v33
	v_mul_f32_e32 v38, v34, v41
	v_mul_f32_e32 v34, v39, v42
	v_mul_f32_e32 v39, v35, v43
	v_fmamk_f32 v35, v152, 0x3b000000, v176
	v_cvt_pk_bf16_f32 v32, v36, v32
	v_mul_f32_e32 v36, 0x4f800000, v35
	v_cmp_gt_f32_e32 vcc, s11, v35
	s_or_b32 s2, s4, 5
	s_ashr_i32 s3, s2, 31
	v_cndmask_b32_e32 v36, v35, v36, vcc
	v_sqrt_f32_e32 v41, v36
	s_lshl_b64 s[2:3], s[2:3], 11
	v_cvt_pk_bf16_f32 v33, v33, v34
; __device__ __forceinline__ unsigned pk2(float lo, float hi) { return pg8::cvt_pk_bf16(lo, hi); }
; __global__ void __launch_bounds__(NWAVES * 64, 2) mk_fwd(Args args) {
;     ...
;             for (int kt = 0, tile = (G == 256) ? 64 * (vcu >> 5) + (vcu & 31) : vcu; tile < T / 64; ++kt, tile = (G == 256) ? ((kt < 2) ? 64 * (vcu >> 5) + 32 * kt + (vcu & 31) : T) : tile + G) {
;     ...
;                     for (int k = 0; k < 8; ++k) { const int tok = wave * 8 + k; const float rstd = 1.0f / sqrtf(sm[k] * (1.f / 512.f) + EPS);
;                         f32x4 x = a[k] * rstd * lg0 + lb0, y = c[k] * rstd * lg1 + lb1;
; #pragma unroll
;                         for (int e = 0; e < 4; ++e) { x[e] = x[e] * __builtin_amdgcn_rcpf(1.f + __builtin_amdgcn_exp2f(-LOG2E * x[e])); y[e] = y[e] * __builtin_amdgcn_rcpf(1.f + __builtin_amdgcn_exp2f(-LOG2E * y[e])); }
;                         bf16* orow = CAT + (size_t)(R0 + tok) * DM;
;                         *(v2u*)(orow + 4 * lane) = (v2u){pk2(x[0], x[1]), pk2(x[2], x[3])}; *(v2u*)(orow + 256 + 4 * lane) = (v2u){pk2(y[0], y[1]), pk2(y[2], y[3])}; }
;                 }
;                 __syncthreads();
	v_lshl_add_u64 v[34:35], v[148:149], 0, s[2:3]
	flat_store_dwordx2 v[34:35], v[32:33]
	v_add_u32_e32 v32, -1, v41
	v_fma_f32 v33, -v32, v41, v36
	v_cmp_ge_f32_e64 s[2:3], 0, v33
	v_add_u32_e32 v33, 1, v41
	s_nop 0
	v_cndmask_b32_e64 v32, v41, v32, s[2:3]
	v_fma_f32 v41, -v33, v41, v36
	v_cmp_lt_f32_e64 s[2:3], 0, v41
	s_nop 1
	v_cndmask_b32_e64 v32, v32, v33, s[2:3]
	v_mul_f32_e32 v33, 0x37800000, v32
	v_cndmask_b32_e32 v32, v32, v33, vcc
	v_cmp_class_f32_e32 vcc, v36, v177
	s_nop 1
	v_cndmask_b32_e32 v36, v32, v36, vcc
	v_div_scale_f32 v41, s[2:3], v36, v36, 1.0
	v_rcp_f32_e32 v42, v41
	v_cvt_pk_bf16_f32 v32, v40, v37
	v_cvt_pk_bf16_f32 v33, v38, v39
	flat_store_dwordx2 v[34:35], v[32:33] offset:512
	v_fma_f32 v32, -v41, v42, 1.0
	v_fmac_f32_e32 v42, v32, v42
	v_div_scale_f32 v32, vcc, 1.0, v36, 1.0
	v_mul_f32_e32 v33, v32, v42
	v_fma_f32 v34, -v41, v33, v32
	v_fmac_f32_e32 v33, v34, v42
	v_fma_f32 v32, -v41, v33, v32
	v_div_fmas_f32 v32, v32, v42, v33
	v_div_fixup_f32 v32, v32, v36, 1.0
	v_pk_mul_f32 v[28:29], v[32:33], v[28:29] op_sel_hi:[0,1]
	v_pk_fma_f32 v[28:29], v[0:1], v[28:29], v[8:9]
	v_pk_mul_f32 v[30:31], v[32:33], v[30:31] op_sel_hi:[0,1]
	v_pk_mul_f32 v[24:25], v[32:33], v[24:25] op_sel_hi:[0,1]
	v_mul_f32_e32 v33, 0xbfb8aa3b, v28
	v_exp_f32_e32 v33, v33
	v_pk_fma_f32 v[24:25], v[4:5], v[24:25], v[12:13]
	v_mul_f32_e32 v34, 0xbfb8aa3b, v29
	v_exp_f32_e32 v34, v34
	v_pk_mul_f32 v[26:27], v[32:33], v[26:27] op_sel_hi:[0,1]
	v_add_f32_e32 v32, 1.0, v33
	v_mul_f32_e32 v33, 0xbfb8aa3b, v24
	v_exp_f32_e32 v33, v33
	v_add_f32_e32 v34, 1.0, v34
	v_mul_f32_e32 v35, 0xbfb8aa3b, v25
	v_rcp_f32_e32 v32, v32
	v_add_f32_e32 v33, 1.0, v33
	v_rcp_f32_e32 v33, v33
	v_rcp_f32_e32 v34, v34
	v_exp_f32_e32 v35, v35
	v_pk_fma_f32 v[30:31], v[2:3], v[30:31], v[10:11]
	v_pk_fma_f32 v[26:27], v[6:7], v[26:27], v[14:15]
	v_mul_f32_e32 v28, v28, v32
	v_mul_f32_e32 v32, v24, v33
	v_mul_f32_e32 v24, v29, v34
	v_add_f32_e32 v29, 1.0, v35
	v_mul_f32_e32 v33, 0xbfb8aa3b, v30
	v_mul_f32_e32 v34, 0xbfb8aa3b, v26
	v_rcp_f32_e32 v29, v29
	v_exp_f32_e32 v33, v33
	v_exp_f32_e32 v34, v34
	v_mul_f32_e32 v35, 0xbfb8aa3b, v27
	v_mul_f32_e32 v29, v25, v29
	v_add_f32_e32 v25, 1.0, v33
	v_add_f32_e32 v33, 1.0, v34
	v_mul_f32_e32 v34, 0xbfb8aa3b, v31
	v_exp_f32_e32 v34, v34
	v_exp_f32_e32 v35, v35
	v_rcp_f32_e32 v25, v25
	v_rcp_f32_e32 v33, v33
	v_add_f32_e32 v34, 1.0, v34
	v_add_f32_e32 v35, 1.0, v35
	v_rcp_f32_e32 v34, v34
	v_rcp_f32_e32 v35, v35
	v_mul_f32_e32 v25, v30, v25
	v_mul_f32_e32 v30, v26, v33
	v_mul_f32_e32 v26, v31, v34
	v_mul_f32_e32 v31, v27, v35
	v_fmamk_f32 v27, v81, 0x3b000000, v176
	v_cvt_pk_bf16_f32 v24, v28, v24
	v_mul_f32_e32 v28, 0x4f800000, v27
	v_cmp_gt_f32_e32 vcc, s11, v27
	s_or_b32 s2, s4, 6
	s_ashr_i32 s3, s2, 31
	v_cndmask_b32_e32 v28, v27, v28, vcc
	v_sqrt_f32_e32 v33, v28
	s_lshl_b64 s[2:3], s[2:3], 11
	v_cvt_pk_bf16_f32 v25, v25, v26
	v_lshl_add_u64 v[26:27], v[148:149], 0, s[2:3]
	flat_store_dwordx2 v[26:27], v[24:25]
	v_add_u32_e32 v24, -1, v33
	v_fma_f32 v25, -v24, v33, v28
	v_cmp_ge_f32_e64 s[2:3], 0, v25
	v_add_u32_e32 v25, 1, v33
	s_nop 0
	v_cndmask_b32_e64 v24, v33, v24, s[2:3]
	v_fma_f32 v33, -v25, v33, v28
	v_cmp_lt_f32_e64 s[2:3], 0, v33
	s_nop 1
	v_cndmask_b32_e64 v24, v24, v25, s[2:3]
	v_mul_f32_e32 v25, 0x37800000, v24
	v_cndmask_b32_e32 v24, v24, v25, vcc
	v_cmp_class_f32_e32 vcc, v28, v177
	s_nop 1
	v_cndmask_b32_e32 v28, v24, v28, vcc
	v_div_scale_f32 v33, s[2:3], v28, v28, 1.0
	v_rcp_f32_e32 v34, v33
	v_cvt_pk_bf16_f32 v24, v32, v29
	v_cvt_pk_bf16_f32 v25, v30, v31
	flat_store_dwordx2 v[26:27], v[24:25] offset:512
	v_fma_f32 v24, -v33, v34, 1.0
	v_fmac_f32_e32 v34, v24, v34
	v_div_scale_f32 v24, vcc, 1.0, v28, 1.0
	v_mul_f32_e32 v25, v24, v34
	v_fma_f32 v26, -v33, v25, v24
	v_fmac_f32_e32 v25, v26, v34
	v_fma_f32 v24, -v33, v25, v24
	v_div_fmas_f32 v24, v24, v34, v25
	v_div_fixup_f32 v24, v24, v28, 1.0
	v_pk_mul_f32 v[20:21], v[24:25], v[20:21] op_sel_hi:[0,1]
	v_pk_fma_f32 v[20:21], v[0:1], v[20:21], v[8:9]
	v_pk_mul_f32 v[22:23], v[24:25], v[22:23] op_sel_hi:[0,1]
	v_pk_mul_f32 v[16:17], v[24:25], v[16:17] op_sel_hi:[0,1]
	v_mul_f32_e32 v25, 0xbfb8aa3b, v20
	v_exp_f32_e32 v25, v25
	v_pk_fma_f32 v[16:17], v[4:5], v[16:17], v[12:13]
	v_mul_f32_e32 v26, 0xbfb8aa3b, v21
	v_exp_f32_e32 v26, v26
	v_pk_mul_f32 v[18:19], v[24:25], v[18:19] op_sel_hi:[0,1]
	v_add_f32_e32 v24, 1.0, v25
	v_mul_f32_e32 v25, 0xbfb8aa3b, v16
	v_exp_f32_e32 v25, v25
	v_add_f32_e32 v26, 1.0, v26
	v_mul_f32_e32 v27, 0xbfb8aa3b, v17
	v_rcp_f32_e32 v24, v24
	v_add_f32_e32 v25, 1.0, v25
	v_rcp_f32_e32 v25, v25
	v_rcp_f32_e32 v26, v26
	v_exp_f32_e32 v27, v27
	v_pk_fma_f32 v[22:23], v[2:3], v[22:23], v[10:11]
	v_pk_fma_f32 v[18:19], v[6:7], v[18:19], v[14:15]
	v_mul_f32_e32 v20, v20, v24
	v_mul_f32_e32 v24, v16, v25
	v_mul_f32_e32 v16, v21, v26
	v_add_f32_e32 v21, 1.0, v27
	v_mul_f32_e32 v25, 0xbfb8aa3b, v22
	v_mul_f32_e32 v26, 0xbfb8aa3b, v18
	v_rcp_f32_e32 v21, v21
	v_exp_f32_e32 v25, v25
	v_exp_f32_e32 v26, v26
	v_mul_f32_e32 v27, 0xbfb8aa3b, v19
	v_mul_f32_e32 v21, v17, v21
	v_add_f32_e32 v17, 1.0, v25
	v_add_f32_e32 v25, 1.0, v26
	v_mul_f32_e32 v26, 0xbfb8aa3b, v23
	v_exp_f32_e32 v26, v26
	v_exp_f32_e32 v27, v27
	v_rcp_f32_e32 v17, v17
	v_rcp_f32_e32 v25, v25
	v_add_f32_e32 v26, 1.0, v26
	v_rcp_f32_e32 v26, v26
	v_add_f32_e32 v27, 1.0, v27
	v_rcp_f32_e32 v27, v27
	s_or_b32 s2, s4, 7
	s_ashr_i32 s3, s2, 31
	s_lshl_b64 s[2:3], s[2:3], 11
	s_add_i32 s4, s13, 1
	v_mul_f32_e32 v17, v22, v17
	v_mul_f32_e32 v22, v18, v25
	v_mul_f32_e32 v18, v23, v26
	s_cmp_eq_u32 s13, 0
	v_mul_f32_e32 v23, v19, v27
	v_cvt_pk_bf16_f32 v16, v20, v16
	v_cvt_pk_bf16_f32 v17, v17, v18
	v_lshl_add_u64 v[18:19], v[148:149], 0, s[2:3]
	s_cselect_b32 s6, s15, 0x8000
	s_and_b64 s[2:3], s[50:51], exec
	s_cselect_b32 s6, s6, s5
	s_cmpk_gt_i32 s6, 0x1ff
	s_mov_b32 s13, s4
	flat_store_dwordx2 v[18:19], v[16:17]
	v_cvt_pk_bf16_f32 v16, v24, v21
	v_cvt_pk_bf16_f32 v17, v22, v23
	flat_store_dwordx2 v[18:19], v[16:17] offset:512
	s_waitcnt lgkmcnt(0)
	s_barrier
	s_cbranch_scc1 .LBB0_361

;     __device__ __forceinline__ void operator()(Acc& acc, const Unit& u, int wr, int wc, int fr, int fq, PG8_LAS unsigned char* xl) const {
;     ...
;             for (int m = 0; m < 4; ++m) { const int rl = ai * HALF + wr * 64 + m * 16 + fr; const float rs = S[rl];
;                 float mx = -INFINITY;
; #pragma unroll
;                 for (int bj = 0; bj < 2; ++bj)
; #pragma unroll
;                     for (int n = 0; n < 2; ++n) { const f32x4 v = acc[ai][bj][m][n] * rs; acc[ai][bj][m][n] = v; mx = fmaxf(mx, fmaxf(fmaxf(v[0], v[1]), fmaxf(v[2], v[3]))); }
;                 mx = fmaxf(mx, __shfl_xor(mx, 16)); mx = fmaxf(mx, __shfl_xor(mx, 32));
;                 float s = 0.f;
; #pragma unroll
;                 for (int bj = 0; bj < 2; ++bj)
; #pragma unroll
;                     for (int n = 0; n < 2; ++n) { f32x4 v = acc[ai][bj][m][n];
; #pragma unroll
;                         for (int e = 0; e < 4; ++e) { v[e] = __builtin_amdgcn_exp2f(v[e] - mx); s += v[e]; }
;                         acc[ai][bj][m][n] = v; }
;                 s += __shfl_xor(s, 16); s += __shfl_xor(s, 32);
;                 if (fq == 0) X[rl * 4 + wc] = (f32x2){mx, s};
.LBB0_582:
	s_or_b64 exec, exec, s[50:51]
	s_waitcnt vmcnt(0) lgkmcnt(0)
	s_barrier
	ds_read_b32 v146, v157
	v_and_b32_e32 v148, 64, v186
	v_xor_b32_e32 v147, 16, v186
	v_add_u32_e32 v150, 64, v148
	v_cmp_lt_i32_e32 vcc, v147, v150
	s_nop 1
	v_cndmask_b32_e32 v147, v186, v147, vcc
	s_waitcnt lgkmcnt(0)
	v_pk_mul_f32 v[126:127], v[126:127], v[146:147] op_sel_hi:[1,0]
	v_lshlrev_b32_e32 v187, 2, v147
	v_pk_mul_f32 v[124:125], v[124:125], v[146:147] op_sel_hi:[1,0]
	v_max_f32_e32 v147, v126, v127
	v_max3_f32 v147, v124, v125, v147
	v_pk_mul_f32 v[122:123], v[122:123], v[146:147] op_sel_hi:[1,0]
	v_pk_mul_f32 v[148:149], v[120:121], v[146:147] op_sel_hi:[1,0]
	v_max_f32_e32 v120, v122, v123
	v_max3_f32 v120, v148, v149, v120
	v_pk_mul_f32 v[118:119], v[118:119], v[146:147] op_sel_hi:[1,0]
	v_pk_mul_f32 v[114:115], v[114:115], v[146:147] op_sel_hi:[1,0]
	v_max3_f32 v120, v147, s75, v120
	v_pk_mul_f32 v[116:117], v[116:117], v[146:147] op_sel_hi:[1,0]
	v_max_f32_e32 v121, v118, v119
	v_pk_mul_f32 v[146:147], v[112:113], v[146:147] op_sel_hi:[1,0]
	v_max_f32_e32 v112, v114, v115
	v_max3_f32 v121, v116, v117, v121
	v_max3_f32 v112, v146, v147, v112
	v_max3_f32 v112, v120, v121, v112
	v_mov_b32_e32 v113, v112
	s_nop 1
	v_permlane16_swap_b32_e32 v112, v113
	v_xor_b32_e32 v120, 32, v186
	v_cmp_lt_i32_e32 vcc, v120, v150
	s_waitcnt lgkmcnt(0)
	v_max_f32_e32 v113, v113, v113
	v_cndmask_b32_e32 v120, v186, v120, vcc
	v_lshlrev_b32_e32 v188, 2, v120
	v_max_f32_e32 v112, v112, v113
	v_mov_b32_e32 v113, v112
	s_nop 1
	v_permlane32_swap_b32_e32 v112, v113
	s_waitcnt lgkmcnt(0)
	v_max_f32_e32 v113, v113, v113
	v_max_f32_e32 v112, v112, v113
	v_sub_f32_e32 v113, v124, v112
	v_exp_f32_e32 v120, v113
	v_sub_f32_e32 v113, v125, v112
	v_exp_f32_e32 v121, v113
	v_sub_f32_e32 v113, v126, v112
	v_exp_f32_e32 v126, v113
	v_sub_f32_e32 v113, v127, v112
	v_exp_f32_e32 v127, v113
	v_sub_f32_e32 v124, v148, v112
	v_add_f32_e32 v113, 0, v120
	v_exp_f32_e32 v124, v124
	v_sub_f32_e32 v125, v149, v112
	v_add_f32_e32 v113, v121, v113
	v_exp_f32_e32 v125, v125
	v_sub_f32_e32 v122, v122, v112
	v_add_f32_e32 v113, v126, v113
	v_exp_f32_e32 v150, v122
	v_sub_f32_e32 v122, v123, v112
	v_add_f32_e32 v113, v127, v113
	v_exp_f32_e32 v151, v122
	v_sub_f32_e32 v116, v116, v112
	v_add_f32_e32 v113, v124, v113
	v_exp_f32_e32 v122, v116
	v_sub_f32_e32 v116, v117, v112
	v_add_f32_e32 v113, v125, v113
	v_exp_f32_e32 v123, v116
	v_sub_f32_e32 v116, v118, v112
	v_add_f32_e32 v113, v150, v113
	v_exp_f32_e32 v148, v116
	v_sub_f32_e32 v116, v119, v112
	v_add_f32_e32 v113, v151, v113
	v_exp_f32_e32 v149, v116
	v_sub_f32_e32 v116, v146, v112
	v_add_f32_e32 v113, v122, v113
	v_exp_f32_e32 v146, v116
	v_sub_f32_e32 v116, v147, v112
	v_add_f32_e32 v113, v123, v113
	v_exp_f32_e32 v147, v116
	v_sub_f32_e32 v114, v114, v112
	v_add_f32_e32 v113, v148, v113
	v_exp_f32_e32 v152, v114
	v_sub_f32_e32 v114, v115, v112
	v_add_f32_e32 v113, v149, v113
	v_exp_f32_e32 v153, v114
	v_add_f32_e32 v113, v146, v113
	v_add_f32_e32 v113, v147, v113
	v_add_f32_e32 v113, v152, v113
	v_add_f32_e32 v113, v153, v113
	v_mov_b32_e32 v114, v113
	s_nop 1
	v_permlane16_swap_b32_e32 v113, v114
	s_waitcnt lgkmcnt(0)
	v_add_f32_e32 v113, v113, v114
	v_mov_b32_e32 v114, v113
	s_nop 1
	v_permlane32_swap_b32_e32 v113, v114
	s_and_saveexec_b64 s[2:3], s[6:7]
	s_cbranch_execz .LBB0_584
	s_waitcnt lgkmcnt(0)
	v_add_f32_e32 v113, v113, v114
	v_add_u32_e32 v114, s67, v158
	ds_write_b64 v114, v[112:113]
.LBB0_584:
	s_or_b64 exec, exec, s[2:3]
	ds_read_b32 v112, v160
	s_waitcnt lgkmcnt(0)
	v_pk_mul_f32 v[110:111], v[110:111], v[112:113] op_sel_hi:[1,0]
	v_pk_mul_f32 v[106:107], v[106:107], v[112:113] op_sel_hi:[1,0]
	v_pk_mul_f32 v[108:109], v[108:109], v[112:113] op_sel_hi:[1,0]
	v_pk_mul_f32 v[114:115], v[104:105], v[112:113] op_sel_hi:[1,0]
	v_max_f32_e32 v104, v110, v111
	v_max_f32_e32 v105, v106, v107
	v_max3_f32 v104, v108, v109, v104
	v_max3_f32 v105, v114, v115, v105
	v_pk_mul_f32 v[102:103], v[102:103], v[112:113] op_sel_hi:[1,0]
	v_pk_mul_f32 v[98:99], v[98:99], v[112:113] op_sel_hi:[1,0]
	v_max3_f32 v104, v104, s75, v105
	v_pk_mul_f32 v[100:101], v[100:101], v[112:113] op_sel_hi:[1,0]
	v_max_f32_e32 v105, v102, v103
	v_pk_mul_f32 v[112:113], v[96:97], v[112:113] op_sel_hi:[1,0]
	v_max_f32_e32 v96, v98, v99
	v_max3_f32 v105, v100, v101, v105
	v_max3_f32 v96, v112, v113, v96
	v_max3_f32 v96, v104, v105, v96
	v_mov_b32_e32 v97, v96
	s_nop 1
	v_permlane16_swap_b32_e32 v96, v97
	s_waitcnt lgkmcnt(0)
	v_max_f32_e32 v97, v97, v97
	v_max_f32_e32 v96, v96, v97
	v_mov_b32_e32 v97, v96
	s_nop 1
	v_permlane32_swap_b32_e32 v96, v97
	s_waitcnt lgkmcnt(0)
	v_max_f32_e32 v97, v97, v97
	v_max_f32_e32 v96, v96, v97
	v_sub_f32_e32 v97, v108, v96
	v_exp_f32_e32 v104, v97
	v_sub_f32_e32 v97, v109, v96
	v_exp_f32_e32 v105, v97
	v_sub_f32_e32 v97, v110, v96
	v_exp_f32_e32 v110, v97
	v_sub_f32_e32 v97, v111, v96
	v_exp_f32_e32 v111, v97
	v_sub_f32_e32 v108, v114, v96
	v_add_f32_e32 v97, 0, v104
	v_exp_f32_e32 v108, v108
	v_sub_f32_e32 v109, v115, v96
	v_add_f32_e32 v97, v105, v97
	v_exp_f32_e32 v109, v109
	v_sub_f32_e32 v106, v106, v96
	v_add_f32_e32 v97, v110, v97
	v_exp_f32_e32 v116, v106
	v_sub_f32_e32 v106, v107, v96
	v_add_f32_e32 v97, v111, v97
	v_exp_f32_e32 v117, v106
	v_sub_f32_e32 v100, v100, v96
	v_add_f32_e32 v97, v108, v97
	v_exp_f32_e32 v106, v100
	v_sub_f32_e32 v100, v101, v96
	v_add_f32_e32 v97, v109, v97
	v_exp_f32_e32 v107, v100
	v_sub_f32_e32 v100, v102, v96
	v_add_f32_e32 v97, v116, v97
	v_exp_f32_e32 v114, v100
	v_sub_f32_e32 v100, v103, v96
	v_add_f32_e32 v97, v117, v97
	v_exp_f32_e32 v115, v100
	v_sub_f32_e32 v100, v112, v96
	v_add_f32_e32 v97, v106, v97
	v_exp_f32_e32 v112, v100
	v_sub_f32_e32 v100, v113, v96
	v_add_f32_e32 v97, v107, v97
	v_exp_f32_e32 v113, v100
	v_sub_f32_e32 v98, v98, v96
	v_add_f32_e32 v97, v114, v97
	v_exp_f32_e32 v118, v98
	v_sub_f32_e32 v98, v99, v96
	v_add_f32_e32 v97, v115, v97
	v_exp_f32_e32 v119, v98
	v_add_f32_e32 v97, v112, v97
	v_add_f32_e32 v97, v113, v97
	v_add_f32_e32 v97, v118, v97
	v_add_f32_e32 v97, v119, v97
	v_mov_b32_e32 v98, v97
	s_nop 1
	v_permlane16_swap_b32_e32 v97, v98
	s_waitcnt lgkmcnt(0)
	v_add_f32_e32 v97, v97, v98
	v_mov_b32_e32 v98, v97
	s_nop 1
	v_permlane32_swap_b32_e32 v97, v98
	s_and_saveexec_b64 s[2:3], s[6:7]
	s_cbranch_execz .LBB0_586
	s_waitcnt lgkmcnt(0)
	v_add_f32_e32 v97, v97, v98
	v_add_u32_e32 v98, s67, v161
	ds_write_b64 v98, v[96:97]
;     __device__ __forceinline__ void operator()(Acc& acc, const Unit& u, int wr, int wc, int fr, int fq, PG8_LAS unsigned char* xl) const {
;     ...
;             for (int m = 0; m < 4; ++m) { const int rl = ai * HALF + wr * 64 + m * 16 + fr; const float rs = S[rl];
;                 float mx = -INFINITY;
; #pragma unroll
;                 for (int bj = 0; bj < 2; ++bj)
; #pragma unroll
;                     for (int n = 0; n < 2; ++n) { const f32x4 v = acc[ai][bj][m][n] * rs; acc[ai][bj][m][n] = v; mx = fmaxf(mx, fmaxf(fmaxf(v[0], v[1]), fmaxf(v[2], v[3]))); }
;                 mx = fmaxf(mx, __shfl_xor(mx, 16)); mx = fmaxf(mx, __shfl_xor(mx, 32));
;                 float s = 0.f;
; #pragma unroll
;                 for (int bj = 0; bj < 2; ++bj)
; #pragma unroll
;                     for (int n = 0; n < 2; ++n) { f32x4 v = acc[ai][bj][m][n];
; #pragma unroll
;                         for (int e = 0; e < 4; ++e) { v[e] = __builtin_amdgcn_exp2f(v[e] - mx); s += v[e]; }
;                         acc[ai][bj][m][n] = v; }
;                 s += __shfl_xor(s, 16); s += __shfl_xor(s, 32);
;                 if (fq == 0) X[rl * 4 + wc] = (f32x2){mx, s};
.LBB0_586:
	s_or_b64 exec, exec, s[2:3]
	ds_read_b32 v96, v163
	s_waitcnt lgkmcnt(0)
	v_pk_mul_f32 v[94:95], v[94:95], v[96:97] op_sel_hi:[1,0]
	v_pk_mul_f32 v[90:91], v[90:91], v[96:97] op_sel_hi:[1,0]
	v_pk_mul_f32 v[92:93], v[92:93], v[96:97] op_sel_hi:[1,0]
	v_pk_mul_f32 v[98:99], v[88:89], v[96:97] op_sel_hi:[1,0]
	v_max_f32_e32 v88, v94, v95
	v_max_f32_e32 v89, v90, v91
	v_max3_f32 v88, v92, v93, v88
	v_max3_f32 v89, v98, v99, v89
	v_pk_mul_f32 v[86:87], v[86:87], v[96:97] op_sel_hi:[1,0]
	v_pk_mul_f32 v[82:83], v[82:83], v[96:97] op_sel_hi:[1,0]
	v_max3_f32 v88, v88, s75, v89
	v_pk_mul_f32 v[84:85], v[84:85], v[96:97] op_sel_hi:[1,0]
	v_max_f32_e32 v89, v86, v87
	v_pk_mul_f32 v[96:97], v[80:81], v[96:97] op_sel_hi:[1,0]
	v_max_f32_e32 v80, v82, v83
	v_max3_f32 v89, v84, v85, v89
	v_max3_f32 v80, v96, v97, v80
	v_max3_f32 v80, v88, v89, v80
	v_mov_b32_e32 v81, v80
	s_nop 1
	v_permlane16_swap_b32_e32 v80, v81
	s_waitcnt lgkmcnt(0)
	v_max_f32_e32 v81, v81, v81
	v_max_f32_e32 v80, v80, v81
	v_mov_b32_e32 v81, v80
	s_nop 1
	v_permlane32_swap_b32_e32 v80, v81
	s_waitcnt lgkmcnt(0)
	v_max_f32_e32 v81, v81, v81
	v_max_f32_e32 v80, v80, v81
	v_sub_f32_e32 v81, v92, v80
	v_exp_f32_e32 v88, v81
	v_sub_f32_e32 v81, v93, v80
	v_exp_f32_e32 v89, v81
	v_sub_f32_e32 v81, v94, v80
	v_exp_f32_e32 v94, v81
	v_sub_f32_e32 v81, v95, v80
	v_exp_f32_e32 v95, v81
	v_sub_f32_e32 v92, v98, v80
	v_add_f32_e32 v81, 0, v88
	v_exp_f32_e32 v92, v92
	v_sub_f32_e32 v93, v99, v80
	v_add_f32_e32 v81, v89, v81
	v_exp_f32_e32 v93, v93
	v_sub_f32_e32 v90, v90, v80
	v_add_f32_e32 v81, v94, v81
	v_exp_f32_e32 v100, v90
	v_sub_f32_e32 v90, v91, v80
	v_add_f32_e32 v81, v95, v81
	v_exp_f32_e32 v101, v90
	v_sub_f32_e32 v84, v84, v80
	v_add_f32_e32 v81, v92, v81
	v_exp_f32_e32 v90, v84
	v_sub_f32_e32 v84, v85, v80
	v_add_f32_e32 v81, v93, v81
	v_exp_f32_e32 v91, v84
	v_sub_f32_e32 v84, v86, v80
	v_add_f32_e32 v81, v100, v81
	v_exp_f32_e32 v98, v84
	v_sub_f32_e32 v84, v87, v80
	v_add_f32_e32 v81, v101, v81
	v_exp_f32_e32 v99, v84
	v_sub_f32_e32 v84, v96, v80
	v_add_f32_e32 v81, v90, v81
	v_exp_f32_e32 v96, v84
	v_sub_f32_e32 v84, v97, v80
	v_add_f32_e32 v81, v91, v81
	v_exp_f32_e32 v97, v84
	v_sub_f32_e32 v82, v82, v80
	v_add_f32_e32 v81, v98, v81
	v_exp_f32_e32 v102, v82
	v_sub_f32_e32 v82, v83, v80
	v_add_f32_e32 v81, v99, v81
	v_exp_f32_e32 v103, v82
	v_add_f32_e32 v81, v96, v81
	v_add_f32_e32 v81, v97, v81
	v_add_f32_e32 v81, v102, v81
	v_add_f32_e32 v81, v103, v81
	v_mov_b32_e32 v82, v81
	s_nop 1
	v_permlane16_swap_b32_e32 v81, v82
	s_waitcnt lgkmcnt(0)
	v_add_f32_e32 v81, v81, v82
	v_mov_b32_e32 v82, v81
	s_nop 1
	v_permlane32_swap_b32_e32 v81, v82
	s_and_saveexec_b64 s[2:3], s[6:7]
	s_cbranch_execz .LBB0_588
	s_waitcnt lgkmcnt(0)
	v_add_f32_e32 v81, v81, v82
	v_add_u32_e32 v82, s67, v164
	ds_write_b64 v82, v[80:81]
.LBB0_588:
	s_or_b64 exec, exec, s[2:3]
	ds_read_b32 v80, v166
	s_waitcnt lgkmcnt(0)
	v_pk_mul_f32 v[78:79], v[78:79], v[80:81] op_sel_hi:[1,0]
	v_pk_mul_f32 v[74:75], v[74:75], v[80:81] op_sel_hi:[1,0]
	v_pk_mul_f32 v[76:77], v[76:77], v[80:81] op_sel_hi:[1,0]
	v_pk_mul_f32 v[82:83], v[72:73], v[80:81] op_sel_hi:[1,0]
	v_max_f32_e32 v72, v78, v79
	v_max_f32_e32 v73, v74, v75
	v_max3_f32 v72, v76, v77, v72
	v_max3_f32 v73, v82, v83, v73
	v_pk_mul_f32 v[70:71], v[70:71], v[80:81] op_sel_hi:[1,0]
	v_pk_mul_f32 v[66:67], v[66:67], v[80:81] op_sel_hi:[1,0]
	v_max3_f32 v72, v72, s75, v73
	v_pk_mul_f32 v[68:69], v[68:69], v[80:81] op_sel_hi:[1,0]
	v_max_f32_e32 v73, v70, v71
	v_pk_mul_f32 v[80:81], v[64:65], v[80:81] op_sel_hi:[1,0]
	v_max_f32_e32 v64, v66, v67
	v_max3_f32 v73, v68, v69, v73
	v_max3_f32 v64, v80, v81, v64
	v_max3_f32 v64, v72, v73, v64
	v_mov_b32_e32 v65, v64
	s_nop 1
	v_permlane16_swap_b32_e32 v64, v65
	s_waitcnt lgkmcnt(0)
	v_max_f32_e32 v65, v65, v65
	v_max_f32_e32 v64, v64, v65
	v_mov_b32_e32 v65, v64
	s_nop 1
	v_permlane32_swap_b32_e32 v64, v65
	s_waitcnt lgkmcnt(0)
	v_max_f32_e32 v65, v65, v65
	v_max_f32_e32 v64, v64, v65
	v_sub_f32_e32 v65, v76, v64
	v_exp_f32_e32 v72, v65
	v_sub_f32_e32 v65, v77, v64
	v_exp_f32_e32 v73, v65
	v_sub_f32_e32 v65, v78, v64
	v_exp_f32_e32 v78, v65
	v_sub_f32_e32 v65, v79, v64
	v_exp_f32_e32 v79, v65
	v_sub_f32_e32 v76, v82, v64
	v_add_f32_e32 v65, 0, v72
	v_exp_f32_e32 v76, v76
	v_sub_f32_e32 v77, v83, v64
	v_add_f32_e32 v65, v73, v65
	v_exp_f32_e32 v77, v77
	v_sub_f32_e32 v74, v74, v64
	v_add_f32_e32 v65, v78, v65
	v_exp_f32_e32 v84, v74
	v_sub_f32_e32 v74, v75, v64
	v_add_f32_e32 v65, v79, v65
	v_exp_f32_e32 v85, v74
	v_sub_f32_e32 v68, v68, v64
	v_add_f32_e32 v65, v76, v65
	v_exp_f32_e32 v74, v68
	v_sub_f32_e32 v68, v69, v64
	v_add_f32_e32 v65, v77, v65
	v_exp_f32_e32 v75, v68
	v_sub_f32_e32 v68, v70, v64
	v_add_f32_e32 v65, v84, v65
	v_exp_f32_e32 v82, v68
	v_sub_f32_e32 v68, v71, v64
	v_add_f32_e32 v65, v85, v65
	v_exp_f32_e32 v83, v68
	v_sub_f32_e32 v68, v80, v64
	v_add_f32_e32 v65, v74, v65
	v_exp_f32_e32 v80, v68
	v_sub_f32_e32 v68, v81, v64
	v_add_f32_e32 v65, v75, v65
	v_exp_f32_e32 v81, v68
	v_sub_f32_e32 v66, v66, v64
	v_add_f32_e32 v65, v82, v65
	v_exp_f32_e32 v86, v66
	v_sub_f32_e32 v66, v67, v64
	v_add_f32_e32 v65, v83, v65
	v_exp_f32_e32 v87, v66
	v_add_f32_e32 v65, v80, v65
	v_add_f32_e32 v65, v81, v65
	v_add_f32_e32 v65, v86, v65
	v_add_f32_e32 v65, v87, v65
	v_mov_b32_e32 v66, v65
	s_nop 1
	v_permlane16_swap_b32_e32 v65, v66
	s_waitcnt lgkmcnt(0)
	v_add_f32_e32 v65, v65, v66
	v_mov_b32_e32 v66, v65
	s_nop 1
	v_permlane32_swap_b32_e32 v65, v66
	s_and_saveexec_b64 s[2:3], s[6:7]
	s_cbranch_execz .LBB0_590
	s_waitcnt lgkmcnt(0)
	v_add_f32_e32 v65, v65, v66
	v_add_u32_e32 v66, s67, v167
	ds_write_b64 v66, v[64:65]
;     __device__ __forceinline__ void operator()(Acc& acc, const Unit& u, int wr, int wc, int fr, int fq, PG8_LAS unsigned char* xl) const {
;     ...
;             for (int m = 0; m < 4; ++m) { const int rl = ai * HALF + wr * 64 + m * 16 + fr; const float rs = S[rl];
;                 float mx = -INFINITY;
; #pragma unroll
;                 for (int bj = 0; bj < 2; ++bj)
; #pragma unroll
;                     for (int n = 0; n < 2; ++n) { const f32x4 v = acc[ai][bj][m][n] * rs; acc[ai][bj][m][n] = v; mx = fmaxf(mx, fmaxf(fmaxf(v[0], v[1]), fmaxf(v[2], v[3]))); }
;                 mx = fmaxf(mx, __shfl_xor(mx, 16)); mx = fmaxf(mx, __shfl_xor(mx, 32));
;                 float s = 0.f;
; #pragma unroll
;                 for (int bj = 0; bj < 2; ++bj)
; #pragma unroll
;                     for (int n = 0; n < 2; ++n) { f32x4 v = acc[ai][bj][m][n];
; #pragma unroll
;                         for (int e = 0; e < 4; ++e) { v[e] = __builtin_amdgcn_exp2f(v[e] - mx); s += v[e]; }
;                         acc[ai][bj][m][n] = v; }
;                 s += __shfl_xor(s, 16); s += __shfl_xor(s, 32);
;                 if (fq == 0) X[rl * 4 + wc] = (f32x2){mx, s};
.LBB0_590:
	s_or_b64 exec, exec, s[2:3]
	ds_read_b32 v64, v169
	s_waitcnt lgkmcnt(0)
	v_pk_mul_f32 v[62:63], v[62:63], v[64:65] op_sel_hi:[1,0]
	v_pk_mul_f32 v[58:59], v[58:59], v[64:65] op_sel_hi:[1,0]
	v_pk_mul_f32 v[60:61], v[60:61], v[64:65] op_sel_hi:[1,0]
	v_pk_mul_f32 v[66:67], v[56:57], v[64:65] op_sel_hi:[1,0]
	v_max_f32_e32 v56, v62, v63
	v_max_f32_e32 v57, v58, v59
	v_max3_f32 v56, v60, v61, v56
	v_max3_f32 v57, v66, v67, v57
	v_pk_mul_f32 v[54:55], v[54:55], v[64:65] op_sel_hi:[1,0]
	v_pk_mul_f32 v[50:51], v[50:51], v[64:65] op_sel_hi:[1,0]
	v_max3_f32 v56, v56, s75, v57
	v_pk_mul_f32 v[52:53], v[52:53], v[64:65] op_sel_hi:[1,0]
	v_max_f32_e32 v57, v54, v55
	v_pk_mul_f32 v[64:65], v[48:49], v[64:65] op_sel_hi:[1,0]
	v_max_f32_e32 v48, v50, v51
	v_max3_f32 v57, v52, v53, v57
	v_max3_f32 v48, v64, v65, v48
	v_max3_f32 v48, v56, v57, v48
	v_mov_b32_e32 v49, v48
	s_nop 1
	v_permlane16_swap_b32_e32 v48, v49
	s_waitcnt lgkmcnt(0)
	v_max_f32_e32 v49, v49, v49
	v_max_f32_e32 v48, v48, v49
	v_mov_b32_e32 v49, v48
	s_nop 1
	v_permlane32_swap_b32_e32 v48, v49
	s_waitcnt lgkmcnt(0)
	v_max_f32_e32 v49, v49, v49
	v_max_f32_e32 v48, v48, v49
	v_sub_f32_e32 v49, v60, v48
	v_exp_f32_e32 v56, v49
	v_sub_f32_e32 v49, v61, v48
	v_exp_f32_e32 v57, v49
	v_sub_f32_e32 v49, v62, v48
	v_exp_f32_e32 v62, v49
	v_sub_f32_e32 v49, v63, v48
	v_exp_f32_e32 v63, v49
	v_sub_f32_e32 v60, v66, v48
	v_add_f32_e32 v49, 0, v56
	v_exp_f32_e32 v60, v60
	v_sub_f32_e32 v61, v67, v48
	v_add_f32_e32 v49, v57, v49
	v_exp_f32_e32 v61, v61
	v_sub_f32_e32 v58, v58, v48
	v_add_f32_e32 v49, v62, v49
	v_exp_f32_e32 v68, v58
	v_sub_f32_e32 v58, v59, v48
	v_add_f32_e32 v49, v63, v49
	v_exp_f32_e32 v69, v58
	v_sub_f32_e32 v52, v52, v48
	v_add_f32_e32 v49, v60, v49
	v_exp_f32_e32 v58, v52
	v_sub_f32_e32 v52, v53, v48
	v_add_f32_e32 v49, v61, v49
	v_exp_f32_e32 v59, v52
	v_sub_f32_e32 v52, v54, v48
	v_add_f32_e32 v49, v68, v49
	v_exp_f32_e32 v66, v52
	v_sub_f32_e32 v52, v55, v48
	v_add_f32_e32 v49, v69, v49
	v_exp_f32_e32 v67, v52
	v_sub_f32_e32 v52, v64, v48
	v_add_f32_e32 v49, v58, v49
	v_exp_f32_e32 v64, v52
	v_sub_f32_e32 v52, v65, v48
	v_add_f32_e32 v49, v59, v49
	v_exp_f32_e32 v65, v52
	v_sub_f32_e32 v50, v50, v48
	v_add_f32_e32 v49, v66, v49
	v_exp_f32_e32 v70, v50
	v_sub_f32_e32 v50, v51, v48
	v_add_f32_e32 v49, v67, v49
	v_exp_f32_e32 v71, v50
	v_add_f32_e32 v49, v64, v49
	v_add_f32_e32 v49, v65, v49
	v_add_f32_e32 v49, v70, v49
	v_add_f32_e32 v49, v71, v49
	v_mov_b32_e32 v50, v49
	s_nop 1
	v_permlane16_swap_b32_e32 v49, v50
	s_waitcnt lgkmcnt(0)
	v_add_f32_e32 v49, v49, v50
	v_mov_b32_e32 v50, v49
	s_nop 1
	v_permlane32_swap_b32_e32 v49, v50
	s_and_saveexec_b64 s[2:3], s[6:7]
	s_cbranch_execz .LBB0_592
	s_waitcnt lgkmcnt(0)
	v_add_f32_e32 v49, v49, v50
	v_add_u32_e32 v50, s67, v170
	ds_write_b64 v50, v[48:49]
.LBB0_592:
	s_or_b64 exec, exec, s[2:3]
	ds_read_b32 v48, v172
	s_waitcnt lgkmcnt(0)
	v_pk_mul_f32 v[46:47], v[46:47], v[48:49] op_sel_hi:[1,0]
	v_pk_mul_f32 v[42:43], v[42:43], v[48:49] op_sel_hi:[1,0]
	v_pk_mul_f32 v[44:45], v[44:45], v[48:49] op_sel_hi:[1,0]
	v_pk_mul_f32 v[50:51], v[40:41], v[48:49] op_sel_hi:[1,0]
	v_max_f32_e32 v40, v46, v47
	v_max_f32_e32 v41, v42, v43
	v_max3_f32 v40, v44, v45, v40
	v_max3_f32 v41, v50, v51, v41
	v_pk_mul_f32 v[38:39], v[38:39], v[48:49] op_sel_hi:[1,0]
	v_pk_mul_f32 v[34:35], v[34:35], v[48:49] op_sel_hi:[1,0]
	v_max3_f32 v40, v40, s75, v41
	v_pk_mul_f32 v[36:37], v[36:37], v[48:49] op_sel_hi:[1,0]
	v_max_f32_e32 v41, v38, v39
	v_pk_mul_f32 v[48:49], v[32:33], v[48:49] op_sel_hi:[1,0]
	v_max_f32_e32 v32, v34, v35
	v_max3_f32 v41, v36, v37, v41
	v_max3_f32 v32, v48, v49, v32
	v_max3_f32 v32, v40, v41, v32
	v_mov_b32_e32 v33, v32
	s_nop 1
	v_permlane16_swap_b32_e32 v32, v33
	s_waitcnt lgkmcnt(0)
	v_max_f32_e32 v33, v33, v33
	v_max_f32_e32 v32, v32, v33
	v_mov_b32_e32 v33, v32
	s_nop 1
	v_permlane32_swap_b32_e32 v32, v33
	s_waitcnt lgkmcnt(0)
	v_max_f32_e32 v33, v33, v33
	v_max_f32_e32 v32, v32, v33
	v_sub_f32_e32 v33, v44, v32
	v_exp_f32_e32 v40, v33
	v_sub_f32_e32 v33, v45, v32
	v_exp_f32_e32 v41, v33
	v_sub_f32_e32 v33, v46, v32
	v_exp_f32_e32 v46, v33
	v_sub_f32_e32 v33, v47, v32
	v_exp_f32_e32 v47, v33
	v_sub_f32_e32 v44, v50, v32
	v_add_f32_e32 v33, 0, v40
	v_exp_f32_e32 v44, v44
	v_sub_f32_e32 v45, v51, v32
	v_add_f32_e32 v33, v41, v33
	v_exp_f32_e32 v45, v45
	v_sub_f32_e32 v42, v42, v32
	v_add_f32_e32 v33, v46, v33
	v_exp_f32_e32 v52, v42
	v_sub_f32_e32 v42, v43, v32
	v_add_f32_e32 v33, v47, v33
	v_exp_f32_e32 v53, v42
	v_sub_f32_e32 v36, v36, v32
	v_add_f32_e32 v33, v44, v33
	v_exp_f32_e32 v42, v36
	v_sub_f32_e32 v36, v37, v32
	v_add_f32_e32 v33, v45, v33
	v_exp_f32_e32 v43, v36
	v_sub_f32_e32 v36, v38, v32
	v_add_f32_e32 v33, v52, v33
	v_exp_f32_e32 v50, v36
	v_sub_f32_e32 v36, v39, v32
	v_add_f32_e32 v33, v53, v33
	v_exp_f32_e32 v51, v36
	v_sub_f32_e32 v36, v48, v32
	v_add_f32_e32 v33, v42, v33
	v_exp_f32_e32 v48, v36
	v_sub_f32_e32 v36, v49, v32
	v_add_f32_e32 v33, v43, v33
	v_exp_f32_e32 v49, v36
	v_sub_f32_e32 v34, v34, v32
	v_add_f32_e32 v33, v50, v33
	v_exp_f32_e32 v54, v34
	v_sub_f32_e32 v34, v35, v32
	v_add_f32_e32 v33, v51, v33
	v_exp_f32_e32 v55, v34
	v_add_f32_e32 v33, v48, v33
	v_add_f32_e32 v33, v49, v33
	v_add_f32_e32 v33, v54, v33
	v_add_f32_e32 v33, v55, v33
	v_mov_b32_e32 v34, v33
	s_nop 1
	v_permlane16_swap_b32_e32 v33, v34
	s_waitcnt lgkmcnt(0)
	v_add_f32_e32 v33, v33, v34
	v_mov_b32_e32 v34, v33
	s_nop 1
	v_permlane32_swap_b32_e32 v33, v34
	s_and_saveexec_b64 s[2:3], s[6:7]
	s_cbranch_execz .LBB0_594
	s_waitcnt lgkmcnt(0)
	v_add_f32_e32 v33, v33, v34
	v_add_u32_e32 v34, s67, v173
	ds_write_b64 v34, v[32:33]
;     __device__ __forceinline__ void operator()(Acc& acc, const Unit& u, int wr, int wc, int fr, int fq, PG8_LAS unsigned char* xl) const {
;     ...
;             for (int m = 0; m < 4; ++m) { const int rl = ai * HALF + wr * 64 + m * 16 + fr; const float rs = S[rl];
;                 float mx = -INFINITY;
; #pragma unroll
;                 for (int bj = 0; bj < 2; ++bj)
; #pragma unroll
;                     for (int n = 0; n < 2; ++n) { const f32x4 v = acc[ai][bj][m][n] * rs; acc[ai][bj][m][n] = v; mx = fmaxf(mx, fmaxf(fmaxf(v[0], v[1]), fmaxf(v[2], v[3]))); }
;                 mx = fmaxf(mx, __shfl_xor(mx, 16)); mx = fmaxf(mx, __shfl_xor(mx, 32));
;                 float s = 0.f;
; #pragma unroll
;                 for (int bj = 0; bj < 2; ++bj)
; #pragma unroll
;                     for (int n = 0; n < 2; ++n) { f32x4 v = acc[ai][bj][m][n];
; #pragma unroll
;                         for (int e = 0; e < 4; ++e) { v[e] = __builtin_amdgcn_exp2f(v[e] - mx); s += v[e]; }
;                         acc[ai][bj][m][n] = v; }
;                 s += __shfl_xor(s, 16); s += __shfl_xor(s, 32);
;                 if (fq == 0) X[rl * 4 + wc] = (f32x2){mx, s};
.LBB0_594:
	s_or_b64 exec, exec, s[2:3]
	ds_read_b32 v32, v175
	s_waitcnt lgkmcnt(0)
	v_pk_mul_f32 v[30:31], v[30:31], v[32:33] op_sel_hi:[1,0]
	v_pk_mul_f32 v[26:27], v[26:27], v[32:33] op_sel_hi:[1,0]
	v_pk_mul_f32 v[28:29], v[28:29], v[32:33] op_sel_hi:[1,0]
	v_pk_mul_f32 v[34:35], v[24:25], v[32:33] op_sel_hi:[1,0]
	v_max_f32_e32 v24, v30, v31
	v_max_f32_e32 v25, v26, v27
	v_max3_f32 v24, v28, v29, v24
	v_max3_f32 v25, v34, v35, v25
	v_pk_mul_f32 v[22:23], v[22:23], v[32:33] op_sel_hi:[1,0]
	v_pk_mul_f32 v[18:19], v[18:19], v[32:33] op_sel_hi:[1,0]
	v_max3_f32 v24, v24, s75, v25
	v_pk_mul_f32 v[20:21], v[20:21], v[32:33] op_sel_hi:[1,0]
	v_max_f32_e32 v25, v22, v23
	v_pk_mul_f32 v[32:33], v[16:17], v[32:33] op_sel_hi:[1,0]
	v_max_f32_e32 v16, v18, v19
	v_max3_f32 v25, v20, v21, v25
	v_max3_f32 v16, v32, v33, v16
	v_max3_f32 v16, v24, v25, v16
	v_mov_b32_e32 v17, v16
	s_nop 1
	v_permlane16_swap_b32_e32 v16, v17
	s_waitcnt lgkmcnt(0)
	v_max_f32_e32 v17, v17, v17
	v_max_f32_e32 v16, v16, v17
	v_mov_b32_e32 v17, v16
	s_nop 1
	v_permlane32_swap_b32_e32 v16, v17
	s_waitcnt lgkmcnt(0)
	v_max_f32_e32 v17, v17, v17
	v_max_f32_e32 v16, v16, v17
	v_sub_f32_e32 v17, v28, v16
	v_exp_f32_e32 v24, v17
	v_sub_f32_e32 v17, v29, v16
	v_exp_f32_e32 v25, v17
	v_sub_f32_e32 v17, v30, v16
	v_exp_f32_e32 v30, v17
	v_sub_f32_e32 v17, v31, v16
	v_exp_f32_e32 v31, v17
	v_sub_f32_e32 v28, v34, v16
	v_add_f32_e32 v17, 0, v24
	v_exp_f32_e32 v28, v28
	v_sub_f32_e32 v29, v35, v16
	v_add_f32_e32 v17, v25, v17
	v_exp_f32_e32 v29, v29
	v_sub_f32_e32 v26, v26, v16
	v_add_f32_e32 v17, v30, v17
	v_exp_f32_e32 v36, v26
	v_sub_f32_e32 v26, v27, v16
	v_add_f32_e32 v17, v31, v17
	v_exp_f32_e32 v37, v26
	v_sub_f32_e32 v20, v20, v16
	v_add_f32_e32 v17, v28, v17
	v_exp_f32_e32 v26, v20
	v_sub_f32_e32 v20, v21, v16
	v_add_f32_e32 v17, v29, v17
	v_exp_f32_e32 v27, v20
	v_sub_f32_e32 v20, v22, v16
	v_add_f32_e32 v17, v36, v17
	v_exp_f32_e32 v34, v20
	v_sub_f32_e32 v20, v23, v16
	v_add_f32_e32 v17, v37, v17
	v_exp_f32_e32 v35, v20
	v_sub_f32_e32 v20, v32, v16
	v_add_f32_e32 v17, v26, v17
	v_exp_f32_e32 v32, v20
	v_sub_f32_e32 v20, v33, v16
	v_add_f32_e32 v17, v27, v17
	v_exp_f32_e32 v33, v20
	v_sub_f32_e32 v18, v18, v16
	v_add_f32_e32 v17, v34, v17
	v_exp_f32_e32 v38, v18
	v_sub_f32_e32 v18, v19, v16
	v_add_f32_e32 v17, v35, v17
	v_exp_f32_e32 v39, v18
	v_add_f32_e32 v17, v32, v17
	v_add_f32_e32 v17, v33, v17
	v_add_f32_e32 v17, v38, v17
	v_add_f32_e32 v17, v39, v17
	v_mov_b32_e32 v18, v17
	s_nop 1
	v_permlane16_swap_b32_e32 v17, v18
	s_waitcnt lgkmcnt(0)
	v_add_f32_e32 v17, v17, v18
	v_mov_b32_e32 v18, v17
	s_nop 1
	v_permlane32_swap_b32_e32 v17, v18
	s_and_saveexec_b64 s[2:3], s[6:7]
	s_cbranch_execz .LBB0_596
	s_waitcnt lgkmcnt(0)
	v_add_f32_e32 v17, v17, v18
	v_add_u32_e32 v18, s67, v176
	ds_write_b64 v18, v[16:17]
.LBB0_596:
	s_or_b64 exec, exec, s[2:3]
	ds_read_b32 v16, v179
	s_waitcnt lgkmcnt(0)
	v_pk_mul_f32 v[14:15], v[14:15], v[16:17] op_sel_hi:[1,0]
	v_pk_mul_f32 v[10:11], v[10:11], v[16:17] op_sel_hi:[1,0]
	v_pk_mul_f32 v[12:13], v[12:13], v[16:17] op_sel_hi:[1,0]
	v_pk_mul_f32 v[18:19], v[8:9], v[16:17] op_sel_hi:[1,0]
	v_max_f32_e32 v8, v14, v15
	v_max_f32_e32 v9, v10, v11
	v_max3_f32 v8, v12, v13, v8
	v_max3_f32 v9, v18, v19, v9
	v_pk_mul_f32 v[6:7], v[6:7], v[16:17] op_sel_hi:[1,0]
	v_pk_mul_f32 v[2:3], v[2:3], v[16:17] op_sel_hi:[1,0]
	v_max3_f32 v8, v8, s75, v9
	v_pk_mul_f32 v[4:5], v[4:5], v[16:17] op_sel_hi:[1,0]
	v_max_f32_e32 v9, v6, v7
	v_pk_mul_f32 v[16:17], v[0:1], v[16:17] op_sel_hi:[1,0]
	v_max_f32_e32 v0, v2, v3
	v_max3_f32 v9, v4, v5, v9
	v_max3_f32 v0, v16, v17, v0
	v_max3_f32 v0, v8, v9, v0
	v_mov_b32_e32 v1, v0
	s_nop 1
	v_permlane16_swap_b32_e32 v0, v1
	s_waitcnt lgkmcnt(0)
	v_max_f32_e32 v1, v1, v1
	v_max_f32_e32 v0, v0, v1
	v_mov_b32_e32 v1, v0
	s_nop 1
	v_permlane32_swap_b32_e32 v0, v1
	s_waitcnt lgkmcnt(0)
	v_max_f32_e32 v1, v1, v1
	v_max_f32_e32 v0, v0, v1
	v_sub_f32_e32 v1, v12, v0
	v_exp_f32_e32 v8, v1
	v_sub_f32_e32 v1, v13, v0
	v_exp_f32_e32 v9, v1
	v_sub_f32_e32 v1, v14, v0
	v_exp_f32_e32 v14, v1
	v_sub_f32_e32 v1, v15, v0
	v_exp_f32_e32 v15, v1
	v_sub_f32_e32 v12, v18, v0
	v_add_f32_e32 v1, 0, v8
	v_exp_f32_e32 v12, v12
	v_sub_f32_e32 v13, v19, v0
	v_add_f32_e32 v1, v9, v1
	v_exp_f32_e32 v13, v13
	v_sub_f32_e32 v10, v10, v0
	v_add_f32_e32 v1, v14, v1
	v_exp_f32_e32 v20, v10
	v_sub_f32_e32 v10, v11, v0
	v_add_f32_e32 v1, v15, v1
	v_exp_f32_e32 v21, v10
	v_sub_f32_e32 v4, v4, v0
	v_add_f32_e32 v1, v12, v1
	v_exp_f32_e32 v10, v4
	v_sub_f32_e32 v4, v5, v0
	v_add_f32_e32 v1, v13, v1
	v_exp_f32_e32 v11, v4
	v_sub_f32_e32 v4, v6, v0
	v_add_f32_e32 v1, v20, v1
	v_exp_f32_e32 v18, v4
	v_sub_f32_e32 v4, v7, v0
	v_add_f32_e32 v1, v21, v1
	v_exp_f32_e32 v19, v4
	v_sub_f32_e32 v4, v16, v0
	v_add_f32_e32 v1, v10, v1
	v_exp_f32_e32 v16, v4
	v_sub_f32_e32 v4, v17, v0
	v_add_f32_e32 v1, v11, v1
	v_exp_f32_e32 v17, v4
	v_sub_f32_e32 v2, v2, v0
	v_add_f32_e32 v1, v18, v1
	v_exp_f32_e32 v22, v2
	v_sub_f32_e32 v2, v3, v0
	v_add_f32_e32 v1, v19, v1
	v_exp_f32_e32 v23, v2
	v_add_f32_e32 v1, v16, v1
	v_add_f32_e32 v1, v17, v1
	v_add_f32_e32 v1, v22, v1
	v_add_f32_e32 v1, v23, v1
	v_mov_b32_e32 v2, v1
	s_nop 1
	v_permlane16_swap_b32_e32 v1, v2
	s_waitcnt lgkmcnt(0)
	v_add_f32_e32 v1, v1, v2
	v_mov_b32_e32 v2, v1
	s_nop 1
	v_permlane32_swap_b32_e32 v1, v2
	s_and_saveexec_b64 s[2:3], s[6:7]
	s_cbranch_execz .LBB0_598
	s_waitcnt lgkmcnt(0)
	v_add_f32_e32 v1, v1, v2
	v_add_u32_e32 v2, s67, v180
	ds_write_b64 v2, v[0:1]
